# hand-written attention main path: 32x32x16 MFMA, K-row permutation so V frags are b128, ring-buffered K frags, counted waits, mid-step LDS fills
# speedup vs baseline: 1.1151x; 1.0997x over previous
; __device__ __forceinline__ int tid_() { int t = threadIdx.x; asm volatile("" : "+v"(t)); return t; }
; __device__ __forceinline__ void attn_item(const Params& p, int b, int h, int qt, float shift, unsigned char* smem) {
;     ...
;   const int t = tid_(), lane = t & 63, wid = t >> 6, l16 = lane & 15, quad = lane >> 4;
;   const int nkeys = (qt < 2) ? CTX : NPOS;
;   const int ntile = nkeys >> 5;
;   const u16* Qp = p.Qall + ((size_t)(b * 4 + h) * NPOS + qt * 128 + wid * 32) * 192;
;   const u16* kp = p.Kb + (size_t)(b * 4 + h) * NPOS * 192 + t * 8;
;   const u16* vp = p.Vt + (size_t)(b * 4 + h) * 128 * NPOS + (size_t)(t >> 2) * NPOS + (t & 3) * 8;
;   const u16* qlane = Qp + (size_t)l16 * 192 + quad * 8;
;   bf16x8 bq[2][6];
; #pragma unroll
;   for (int qi = 0; qi < 2; ++qi)
; #pragma unroll
;     for (int ks = 0; ks < 6; ++ks) bq[qi][ks] = *(const bf16x8*)(qlane + qi * 16 * 192 + ks * 32);
;   f32x4 o[8][2];
; #pragma unroll
;   for (int vt = 0; vt < 8; ++vt)
; #pragma unroll
;     for (int qi = 0; qi < 2; ++qi) o[vt][qi] = (f32x4){0.f, 0.f, 0.f, 0.f};
;   float lrun0 = 0.f, lrun1 = 0.f;
;   u32x4 rk[3], rv[2];
;   f32x4 sA[2][2], sB[2][2];
;     ...
;   __syncthreads();
;   ATT_LOAD(0);
;   ATT_STORE(0);
;   ATT_LOAD(1);
;   __syncthreads();
.LBB0_766:
	s_cmp_eq_u64 s[38:39], 0
	s_cbranch_scc1 .Lfa_item
	v_mov_b32_e32 v70, v187
	v_mov_b64_e32 v[6:7], s[4:5]
	global_load_dwordx4 v[54:57], v[6:7], off offset:344
	s_lshl_b32 s47, s50, 7
	s_addk_i32 s47, 0x100
	s_ashr_i32 s1, s47, 31
	v_ashrrev_i32_e32 v0, 1, v70
	s_add_u32 s0, s9, s47
	v_and_b32_e32 v190, 0xffffffe0, v0
	s_addc_u32 s1, 0, s1
	v_ashrrev_i32_e32 v191, 31, v190
	v_lshl_add_u64 v[8:9], s[0:1], 0, v[190:191]
	v_and_b32_e32 v189, 15, v70
	v_mul_u32_u24_e32 v0, 0xc0, v189
	v_bfe_u32 v12, v70, 4, 2
	v_lshlrev_b32_e32 v0, 1, v0
	v_lshlrev_b32_e32 v58, 3, v70
	v_ashrrev_i32_e32 v59, 31, v58
	v_lshlrev_b32_e32 v188, 3, v12
	v_ashrrev_i32_e32 v71, 2, v70
	v_and_b32_e32 v191, 24, v58
	v_lshlrev_b32_e32 v66, 1, v191
	v_mov_b32_e32 v67, v1
	s_cmp_lt_i32 s50, 0
	v_lshlrev_b32_e32 v237, 4, v70
	s_cselect_b32 s55, 8, 0x108
	s_mov_b32 s51, 0
	s_mov_b32 s52, 1
	s_mov_b32 s53, 3
	s_mov_b32 s54, 2
	s_add_i32 s56, s55, -1
	v_mul_u32_u24_e32 v208, 0x50, v189
	s_mov_b32 s57, 0
	s_waitcnt vmcnt(0) lgkmcnt(0)
	v_mad_u64_u32 v[10:11], s[0:1], v8, s20, v[56:57]
	global_load_dwordx2 v[56:57], v[6:7], off offset:360
	v_mad_i32_i24 v11, v9, s20, v11
	v_lshl_add_u64 v[6:7], v[10:11], 0, v[0:1]
	v_lshlrev_b32_e32 v0, 4, v12
	v_lshl_add_u64 v[10:11], v[6:7], 0, v[0:1]
	global_load_dwordx4 v[46:49], v[10:11], off
	global_load_dwordx4 v[34:37], v[10:11], off offset:64
	global_load_dwordx4 v[30:33], v[10:11], off offset:128
	global_load_dwordx4 v[18:21], v[10:11], off offset:192
	global_load_dwordx4 v[14:17], v[10:11], off offset:256
	global_load_dwordx4 v[6:9], v[10:11], off offset:320
	v_add_co_u32_e32 v10, vcc, s84, v10
	v_lshl_add_u64 v[54:55], v[54:55], 0, s[42:43]
	s_nop 0
	v_addc_co_u32_e32 v11, vcc, 0, v11, vcc
	global_load_dwordx4 v[50:53], v[10:11], off offset:2048
	global_load_dwordx4 v[42:45], v[10:11], off offset:2112
	global_load_dwordx4 v[38:41], v[10:11], off offset:2176
	global_load_dwordx4 v[26:29], v[10:11], off offset:2240
	global_load_dwordx4 v[22:25], v[10:11], off offset:2304
	s_nop 0
	global_load_dwordx4 v[10:13], v[10:11], off offset:2368
	s_waitcnt lgkmcnt(0)
	s_barrier
	v_mad_i64_i32 v[68:69], s[0:1], v71, s68, v[54:55]
	v_lshl_add_u64 v[194:195], v[68:69], 0, v[66:67]
	global_load_dwordx4 v[72:75], v[194:195], off
	s_mov_b32 s0, 0x2aaaaaab
	v_mul_hi_i32 v67, v70, s0
	v_lshrrev_b32_e32 v80, 31, v67
	v_ashrrev_i32_e32 v67, 2, v67
	v_add_u32_e32 v100, v67, v80
	v_mul_lo_u32 v67, v100, 24
	v_sub_u32_e32 v67, v70, v67
	v_mul_lo_u32 v209, v100, s73
	v_lshlrev_b32_e32 v210, 4, v67
	v_add_u32_e32 v101, v209, v210
	v_mad_u32_u24 v106, v189, s73, v0
	v_and_b32_e32 v0, 3, v70
	v_lshlrev_b32_e32 v0, 4, v0
	v_add_u32_e32 v244, 0xb800, v106
	v_add_u32_e32 v245, 0x5c00, v106
	s_waitcnt vmcnt(0)
	v_lshl_add_u64 v[56:57], v[56:57], 0, s[40:41]
	v_lshl_add_u64 v[192:193], v[58:59], 1, v[56:57]
	global_load_dwordx4 v[62:65], v[192:193], off
	v_add_co_u32_e32 v54, vcc, s84, v192
	s_nop 1
	v_addc_co_u32_e32 v55, vcc, 0, v193, vcc
	global_load_dwordx4 v[58:61], v[54:55], off
	v_add_co_u32_e32 v54, vcc, s70, v192
	s_nop 1
	v_addc_co_u32_e32 v55, vcc, 0, v193, vcc
	global_load_dwordx4 v[54:57], v[54:55], off
	v_add_co_u32_e32 v68, vcc, s72, v194
	s_nop 1
	v_addc_co_u32_e32 v69, vcc, 0, v195, vcc
	global_load_dwordx4 v[76:79], v[68:69], off
	s_waitcnt vmcnt(0) lgkmcnt(0)
	ds_write_b128 v101, v[62:65]
	v_add_u32_e32 v62, 0x100, v70
	v_mul_hi_i32 v63, v62, s0
	v_lshrrev_b32_e32 v64, 31, v63
	v_ashrrev_i32_e32 v63, 2, v63
	v_add_u32_e32 v102, v63, v64
	v_mul_lo_u32 v63, v102, 24
	v_sub_u32_e32 v62, v62, v63
	v_mul_lo_u32 v211, v102, s73
	v_lshlrev_b32_e32 v212, 4, v62
	v_add_u32_e32 v103, v211, v212
	ds_write_b128 v103, v[58:61]
	v_add_u32_e32 v58, 0x200, v70
	v_mul_hi_i32 v59, v58, s0
	v_lshrrev_b32_e32 v60, 31, v59
	v_ashrrev_i32_e32 v59, 2, v59
	v_add_u32_e32 v104, v59, v60
	v_mul_lo_u32 v59, v104, 24
	v_sub_u32_e32 v58, v58, v59
	v_mul_lo_u32 v213, v104, s73
	v_lshlrev_b32_e32 v235, 4, v58
	s_movk_i32 s0, 0x50
	v_add_u32_e32 v105, v213, v235
	v_mul_lo_u32 v236, v71, s0
	s_movk_i32 s0, 0x3000
	ds_write_b128 v105, v[54:57]
	v_add_u32_e32 v71, v66, v236
	v_add_co_u32_e32 v54, vcc, s0, v192
	ds_write_b128 v71, v[72:75] offset:13312
	ds_write_b128 v71, v[76:79] offset:18432
	v_addc_co_u32_e32 v55, vcc, 0, v193, vcc
	global_load_dwordx4 v[72:75], v[54:55], off
	v_add_co_u32_e32 v54, vcc, s69, v192
	s_movk_i32 s0, 0x5000
	s_nop 0
	v_addc_co_u32_e32 v55, vcc, 0, v193, vcc
	global_load_dwordx4 v[76:79], v[54:55], off
	v_add_co_u32_e32 v54, vcc, s0, v192
	v_lshlrev_b32_e32 v70, 5, v104
	s_nop 0
	v_addc_co_u32_e32 v55, vcc, 0, v193, vcc
	global_load_dwordx4 v[80:83], v[54:55], off
	global_load_dwordx4 v[84:87], v[194:195], off offset:64
	global_load_dwordx4 v[88:91], v[68:69], off offset:64
	s_waitcnt lgkmcnt(0)
	s_barrier
; __device__ __forceinline__ void attn_item(const Params& p, int b, int h, int qt, float shift, unsigned char* smem) {
;     ...
;   f32x4 o[8][2];
; #pragma unroll
;   for (int vt = 0; vt < 8; ++vt)
; #pragma unroll
;     for (int qi = 0; qi < 2; ++qi) o[vt][qi] = (f32x4){0.f, 0.f, 0.f, 0.f};
;     ...
;   ATT_S(sA, 0);
;   ATT_STORE(1);
;   __syncthreads();
	ds_read_b128 v[54:57], v106
	ds_read_b128 v[92:95], v106 offset:64
	s_waitcnt lgkmcnt(0)
	v_mfma_f32_16x16x32_bf16 v[58:61], v[54:57], v[46:49], 0
	ds_read_b128 v[62:65], v106 offset:6656
	ds_read_b128 v[96:99], v106 offset:320
	v_add_u32_e32 v238, 0x13400, v70
	v_mfma_f32_16x16x32_bf16 v[54:57], v[54:57], v[50:53], 0
	v_add_u32_e32 v243, 0xd800, v70
	v_mov_b32_e32 v70, 0
	v_mov_b32_e32 v110, v70
	v_mfma_f32_16x16x32_bf16 v[58:61], v[92:95], v[34:37], v[58:61]
	v_mov_b32_e32 v111, v70
	v_mov_b32_e32 v112, v70
	v_mov_b32_e32 v113, v70
	v_mfma_f32_16x16x32_bf16 v[54:57], v[92:95], v[42:45], v[54:57]
	ds_read_b128 v[92:95], v106 offset:6720
	v_mov_b32_e32 v114, v70
	v_mov_b32_e32 v115, v70
	s_waitcnt lgkmcnt(0)
	v_mfma_f32_16x16x32_bf16 v[66:69], v[62:65], v[46:49], 0
	v_mov_b32_e32 v116, v70
	v_mov_b32_e32 v117, v70
	v_mov_b32_e32 v104, v70
	v_mfma_f32_16x16x32_bf16 v[62:65], v[62:65], v[50:53], 0
	v_mov_b32_e32 v107, v70
	v_mov_b32_e32 v108, v70
	v_mov_b32_e32 v109, v70
	v_mfma_f32_16x16x32_bf16 v[66:69], v[92:95], v[34:37], v[66:69]
	v_mov_b32_e32 v118, v70
	v_mov_b32_e32 v119, v70
	v_mov_b32_e32 v120, v70
	v_mfma_f32_16x16x32_bf16 v[62:65], v[92:95], v[42:45], v[62:65]
	ds_read_b128 v[92:95], v106 offset:128
	v_mov_b32_e32 v121, v70
	v_mov_b32_e32 v122, v70
	s_waitcnt lgkmcnt(0)
	v_mfma_f32_16x16x32_bf16 v[58:61], v[92:95], v[30:33], v[58:61]
	v_mov_b32_e32 v123, v70
	v_mov_b32_e32 v124, v70
	v_mov_b32_e32 v125, v70
	v_mfma_f32_16x16x32_bf16 v[54:57], v[92:95], v[38:41], v[54:57]
	ds_read_b128 v[92:95], v106 offset:6784
	v_mov_b32_e32 v126, v70
	v_mov_b32_e32 v127, v70
	s_waitcnt lgkmcnt(0)
	v_mfma_f32_16x16x32_bf16 v[66:69], v[92:95], v[30:33], v[66:69]
	v_mov_b32_e32 v128, v70
	v_mov_b32_e32 v129, v70
	v_mov_b32_e32 v130, v70
	v_mfma_f32_16x16x32_bf16 v[62:65], v[92:95], v[38:41], v[62:65]
	ds_read_b128 v[92:95], v106 offset:192
	v_mov_b32_e32 v131, v70
	v_mov_b32_e32 v132, v70
	s_waitcnt lgkmcnt(0)
	v_mfma_f32_16x16x32_bf16 v[58:61], v[92:95], v[18:21], v[58:61]
	v_mov_b32_e32 v133, v70
	v_mov_b32_e32 v196, v70
	v_mov_b32_e32 v197, v70
	v_mfma_f32_16x16x32_bf16 v[54:57], v[92:95], v[26:29], v[54:57]
	ds_read_b128 v[92:95], v106 offset:6848
	s_waitcnt lgkmcnt(0)
	v_mfma_f32_16x16x32_bf16 v[66:69], v[92:95], v[18:21], v[66:69]
	v_mfma_f32_16x16x32_bf16 v[62:65], v[92:95], v[26:29], v[62:65]
	ds_read_b128 v[92:95], v106 offset:256
	s_waitcnt lgkmcnt(0)
	v_mfma_f32_16x16x32_bf16 v[58:61], v[92:95], v[14:17], v[58:61]
	v_mfma_f32_16x16x32_bf16 v[54:57], v[92:95], v[22:25], v[54:57]
	ds_read_b128 v[92:95], v106 offset:6912
	s_waitcnt lgkmcnt(0)
	v_mfma_f32_16x16x32_bf16 v[66:69], v[92:95], v[14:17], v[66:69]
	v_mfma_f32_16x16x32_bf16 v[92:95], v[92:95], v[22:25], v[62:65]
	v_mfma_f32_16x16x32_bf16 v[62:65], v[96:99], v[6:9], v[58:61]
	s_nop 2
	ds_read_b128 v[58:61], v106 offset:6976
	v_mfma_f32_16x16x32_bf16 v[54:57], v[96:99], v[10:13], v[54:57]
	s_waitcnt vmcnt(0)
	ds_write_b128 v101, v[72:75] offset:23552
	ds_write_b128 v103, v[76:79] offset:23552
	ds_write_b128 v105, v[80:83] offset:23552
	ds_write_b128 v71, v[84:87] offset:36864
	ds_write_b128 v71, v[88:91] offset:41984
	v_lshlrev_b32_e32 v71, 5, v102
	v_lshlrev_b32_e32 v72, 5, v100
	s_waitcnt lgkmcnt(5)
	v_mfma_f32_16x16x32_bf16 v[66:69], v[58:61], v[6:9], v[66:69]
	v_add_u32_e32 v239, 0x12400, v71
	v_add_u32_e32 v240, 0x11400, v72
	v_add_u32_e32 v241, 0xb800, v72
	v_mfma_f32_16x16x32_bf16 v[58:61], v[58:61], v[10:13], v[92:95]
	v_add_u32_e32 v242, 0xc800, v71
	v_mov_b32_e32 v71, v70
	v_mov_b32_e32 v72, v70
	v_mov_b32_e32 v73, v70
	v_mov_b32_e32 v74, v70
	v_mov_b32_e32 v75, v70
	v_mov_b32_e32 v76, v70
	v_mov_b32_e32 v77, v70
	v_mov_b32_e32 v78, v70
	v_mov_b32_e32 v79, v70
	v_mov_b32_e32 v80, v70
	v_mov_b32_e32 v81, v70
	v_mov_b32_e32 v82, v70
	v_mov_b32_e32 v83, v70
	v_mov_b32_e32 v84, v70
	v_mov_b32_e32 v85, v70
	v_mov_b32_e32 v90, v70
	v_mov_b32_e32 v91, v70
	v_mov_b32_e32 v92, v70
	v_mov_b32_e32 v93, v70
	v_mov_b32_e32 v98, v70
	v_mov_b32_e32 v99, v70
	v_mov_b32_e32 v100, v70
	v_mov_b32_e32 v101, v70
	v_mov_b32_e32 v86, v70
	v_mov_b32_e32 v87, v70
	v_mov_b32_e32 v88, v70
	v_mov_b32_e32 v89, v70
	v_mov_b32_e32 v94, v70
	v_mov_b32_e32 v95, v70
	v_mov_b32_e32 v96, v70
	v_mov_b32_e32 v97, v70
	v_mov_b32_e32 v102, v70
	v_mov_b32_e32 v103, v70
	v_mov_b32_e32 v105, v70
	v_mov_b32_e32 v106, v70
	s_waitcnt lgkmcnt(0)
	s_barrier
	s_branch .LBB0_768

; __device__ __forceinline__ int tid_() { int t = threadIdx.x; asm volatile("" : "+v"(t)); return t; }
; __device__ __forceinline__ void attn_item(const Params& p, int b, int h, int qt, float shift, unsigned char* smem) {
;     ...
;   const int t = tid_(), lane = t & 63, wid = t >> 6, l16 = lane & 15, quad = lane >> 4;
;   const int nkeys = (qt < 2) ? CTX : NPOS;
;   const int ntile = nkeys >> 5;
;   const u16* Qp = p.Qall + ((size_t)(b * 4 + h) * NPOS + qt * 128 + wid * 32) * 192;
;   const u16* kp = p.Kb + (size_t)(b * 4 + h) * NPOS * 192 + t * 8;
;   const u16* vp = p.Vt + (size_t)(b * 4 + h) * 128 * NPOS + (size_t)(t >> 2) * NPOS + (t & 3) * 8;
;   const u16* qlane = Qp + (size_t)l16 * 192 + quad * 8;
;   bf16x8 bq[2][6];
; #pragma unroll
;   for (int qi = 0; qi < 2; ++qi)
; #pragma unroll
;     for (int ks = 0; ks < 6; ++ks) bq[qi][ks] = *(const bf16x8*)(qlane + qi * 16 * 192 + ks * 32);
;   f32x4 o[8][2];
; #pragma unroll
;   for (int vt = 0; vt < 8; ++vt)
; #pragma unroll
;     for (int qi = 0; qi < 2; ++qi) o[vt][qi] = (f32x4){0.f, 0.f, 0.f, 0.f};
;   float lrun0 = 0.f, lrun1 = 0.f;
;   u32x4 rk[3], rv[2];
;   f32x4 sA[2][2], sB[2][2];
;     ...
;   __syncthreads();
;   ATT_LOAD(0);
;   ATT_STORE(0);
;   ATT_LOAD(1);
;   __syncthreads();
.Lfa_item:
	s_load_dwordx4 s[52:55], s[4:5], 0x158
	s_load_dwordx2 s[56:57], s[4:5], 0x168
	s_load_dwordx2 s[88:89], s[4:5], 0x128
	v_lshrrev_b32_e32 v0, 6, v187
	v_and_b32_e32 v118, 63, v187
	v_and_b32_e32 v119, 31, v118
	v_lshrrev_b32_e32 v120, 5, v118
	v_readfirstlane_b32 s0, v0
	v_and_b32_e32 v121, 0x13, v119
	v_and_b32_e32 v122, 4, v119
	v_lshl_or_b32 v121, v122, 1, v121
	v_and_b32_e32 v122, 8, v119
	v_lshrrev_b32_e32 v122, 1, v122
	v_or_b32_e32 v121, v121, v122
	v_mul_u32_u24_e32 v121, 0x190, v121
	v_lshl_add_u32 v212, v120, 4, v121
	v_mul_u32_u24_e32 v122, 0x50, v119
	v_lshl_add_u32 v122, v120, 4, v122
	v_add_u32_e32 v213, 0x3200, v122
	v_mul_u32_u24_e32 v122, 0x180, v119
	v_lshl_add_u32 v123, v120, 4, v122
	v_lshlrev_b32_e32 v248, 4, v187
	v_lshrrev_b32_e32 v124, 2, v187
	v_and_b32_e32 v125, 3, v187
	v_mul_u32_u24_e32 v126, 0x4200, v124
	v_lshl_add_u32 v235, v125, 4, v126
	v_mul_u32_u24_e32 v126, 0x50, v124
	v_lshl_add_u32 v126, v125, 4, v126
	v_add_u32_e32 v247, 0x3200, v126
	v_mov_b32_e32 v127, v187
	v_mul_u32_u24_e32 v128, 0xaab, v127
	v_lshrrev_b32_e32 v128, 16, v128
	v_add_lshl_u32 v244, v127, v128, 4
	v_add_u32_e32 v127, 0x100, v187
	v_mul_u32_u24_e32 v128, 0xaab, v127
	v_lshrrev_b32_e32 v128, 16, v128
	v_add_lshl_u32 v245, v127, v128, 4
	v_add_u32_e32 v127, 0x200, v187
	v_mul_u32_u24_e32 v128, 0xaab, v127
	v_lshrrev_b32_e32 v128, 16, v128
	v_add_lshl_u32 v246, v127, v128, 4
	s_waitcnt lgkmcnt(0)
	s_nop 3
	s_lshl_b32 s1, s50, 7
	s_addk_i32 s1, 0x100
	s_lshl_b32 s34, s0, 5
	s_add_i32 s1, s1, s34
	s_add_i32 s34, s1, s9
	s_mul_i32 s34, s34, 0x180
	s_add_u32 s54, s54, s34
	s_addc_u32 s55, s55, 0
	s_add_i32 s34, s48, s1
	s_lshl_b32 s34, s34, 11
	s_add_i32 s34, s34, s46
	s_addk_i32 s34, 0x400
	s_add_u32 s88, s88, s34
	s_addc_u32 s89, s89, 0
	s_add_u32 s56, s56, s40
	s_addc_u32 s57, s57, 0
	s_add_u32 s98, s56, 0x2000
	s_addc_u32 s99, s57, 0
	s_add_u32 s52, s52, s42
	s_addc_u32 s53, s53, 0
	s_add_u32 s100, s52, 0x108000
	s_addc_u32 s101, s53, 0
	s_barrier
	global_load_dwordx4 v[208:211], v248, s[56:57]
	global_load_dwordx4 v[216:219], v248, s[98:99] offset:-4096
	global_load_dwordx4 v[220:223], v248, s[98:99]
	global_load_dwordx4 v[236:239], v235, s[52:53]
	global_load_dwordx4 v[240:243], v235, s[100:101]
	global_load_dwordx4 v[6:9], v123, s[54:55] offset:0
	global_load_dwordx4 v[10:13], v123, s[54:55] offset:32
	global_load_dwordx4 v[14:17], v123, s[54:55] offset:64
	global_load_dwordx4 v[18:21], v123, s[54:55] offset:96
	global_load_dwordx4 v[22:25], v123, s[54:55] offset:128
	global_load_dwordx4 v[26:29], v123, s[54:55] offset:160
	global_load_dwordx4 v[30:33], v123, s[54:55] offset:192
	global_load_dwordx4 v[34:37], v123, s[54:55] offset:224
	global_load_dwordx4 v[38:41], v123, s[54:55] offset:256
	global_load_dwordx4 v[42:45], v123, s[54:55] offset:288
	global_load_dwordx4 v[46:49], v123, s[54:55] offset:320
	global_load_dwordx4 v[50:53], v123, s[54:55] offset:352
	s_add_u32 s56, s56, 0x3000
	s_addc_u32 s57, s57, 0
	s_add_u32 s98, s98, 0x3000
	s_addc_u32 s99, s99, 0
	s_add_u32 s52, s52, 64
	s_addc_u32 s53, s53, 0
	s_add_u32 s100, s100, 64
	s_addc_u32 s101, s101, 0
	s_waitcnt vmcnt(16)
	ds_write_b128 v244, v[208:211] offset:0
	s_waitcnt vmcnt(15)
	ds_write_b128 v245, v[216:219] offset:0
	s_waitcnt vmcnt(14)
	ds_write_b128 v246, v[220:223] offset:0
	s_waitcnt vmcnt(13)
	ds_write_b128 v247, v[236:239] offset:0
	s_waitcnt vmcnt(12)
	ds_write_b128 v247, v[240:243] offset:5120
	global_load_dwordx4 v[208:211], v248, s[56:57]
	global_load_dwordx4 v[216:219], v248, s[98:99] offset:-4096
	global_load_dwordx4 v[220:223], v248, s[98:99]
	global_load_dwordx4 v[236:239], v235, s[52:53]
	global_load_dwordx4 v[240:243], v235, s[100:101]
	s_add_u32 s56, s56, 0x3000
	s_addc_u32 s57, s57, 0
	s_add_u32 s98, s98, 0x3000
	s_addc_u32 s99, s99, 0
	s_add_u32 s52, s52, 64
	s_addc_u32 s53, s53, 0
	s_add_u32 s100, s100, 64
	s_addc_u32 s101, s101, 0
	v_mov_b32_e32 v0, 0
	v_mov_b32_e32 v54, 0
	v_mov_b32_e32 v55, 0
	v_mov_b32_e32 v56, 0
	v_mov_b32_e32 v57, 0
	v_mov_b32_e32 v58, 0
	v_mov_b32_e32 v59, 0
	v_mov_b32_e32 v60, 0
	v_mov_b32_e32 v61, 0
	v_mov_b32_e32 v62, 0
	v_mov_b32_e32 v63, 0
	v_mov_b32_e32 v64, 0
	v_mov_b32_e32 v65, 0
	v_mov_b32_e32 v66, 0
	v_mov_b32_e32 v67, 0
	v_mov_b32_e32 v68, 0
	v_mov_b32_e32 v69, 0
	v_mov_b32_e32 v70, 0
	v_mov_b32_e32 v71, 0
	v_mov_b32_e32 v72, 0
	v_mov_b32_e32 v73, 0
	v_mov_b32_e32 v74, 0
	v_mov_b32_e32 v75, 0
	v_mov_b32_e32 v76, 0
	v_mov_b32_e32 v77, 0
	v_mov_b32_e32 v78, 0
	v_mov_b32_e32 v79, 0
	v_mov_b32_e32 v80, 0
	v_mov_b32_e32 v81, 0
	v_mov_b32_e32 v82, 0
	v_mov_b32_e32 v83, 0
	v_mov_b32_e32 v84, 0
	v_mov_b32_e32 v85, 0
	v_mov_b32_e32 v86, 0
	v_mov_b32_e32 v87, 0
	v_mov_b32_e32 v88, 0
	v_mov_b32_e32 v89, 0
	v_mov_b32_e32 v90, 0
	v_mov_b32_e32 v91, 0
	v_mov_b32_e32 v92, 0
	v_mov_b32_e32 v93, 0
	v_mov_b32_e32 v94, 0
	v_mov_b32_e32 v95, 0
	v_mov_b32_e32 v96, 0
	v_mov_b32_e32 v97, 0
	v_mov_b32_e32 v98, 0
	v_mov_b32_e32 v99, 0
	v_mov_b32_e32 v100, 0
	v_mov_b32_e32 v101, 0
	v_mov_b32_e32 v102, 0
	v_mov_b32_e32 v103, 0
	v_mov_b32_e32 v104, 0
	v_mov_b32_e32 v105, 0
	v_mov_b32_e32 v106, 0
	v_mov_b32_e32 v107, 0
	v_mov_b32_e32 v108, 0
	v_mov_b32_e32 v109, 0
	v_mov_b32_e32 v110, 0
	v_mov_b32_e32 v111, 0
	v_mov_b32_e32 v112, 0
	v_mov_b32_e32 v113, 0
	v_mov_b32_e32 v114, 0
	v_mov_b32_e32 v115, 0
	v_mov_b32_e32 v116, 0
	v_mov_b32_e32 v117, 0
	s_waitcnt vmcnt(4)
	ds_write_b128 v244, v[208:211] offset:23040
	s_waitcnt vmcnt(3)
	ds_write_b128 v245, v[216:219] offset:23040
	s_waitcnt vmcnt(2)
	ds_write_b128 v246, v[220:223] offset:23040
	s_waitcnt vmcnt(1)
	ds_write_b128 v247, v[236:239] offset:23040
	s_waitcnt vmcnt(0)
	ds_write_b128 v247, v[240:243] offset:28160
	global_load_dwordx4 v[208:211], v248, s[56:57]
	global_load_dwordx4 v[216:219], v248, s[98:99] offset:-4096
	global_load_dwordx4 v[220:223], v248, s[98:99]
	global_load_dwordx4 v[236:239], v235, s[52:53]
	global_load_dwordx4 v[240:243], v235, s[100:101]
	s_add_u32 s56, s56, 0x3000
	s_addc_u32 s57, s57, 0
	s_add_u32 s98, s98, 0x3000
	s_addc_u32 s99, s99, 0
	s_add_u32 s52, s52, 64
	s_addc_u32 s53, s53, 0
	s_add_u32 s100, s100, 64
	s_addc_u32 s101, s101, 0
	s_waitcnt lgkmcnt(0)
	s_barrier
	ds_read_b128 v[150:153], v212 offset:0
	ds_read_b128 v[154:157], v212 offset:32
	ds_read_b128 v[158:161], v212 offset:64
	ds_read_b128 v[162:165], v212 offset:96
	ds_read_b128 v[166:169], v212 offset:128
	ds_read_b128 v[170:173], v212 offset:160
	s_waitcnt lgkmcnt(5)
	v_mfma_f32_32x32x16_bf16 v[118:133], v[150:153], v[6:9], 0
	ds_read_b128 v[150:153], v212 offset:192
	s_waitcnt lgkmcnt(5)
	v_mfma_f32_32x32x16_bf16 v[118:133], v[154:157], v[10:13], v[118:133]
	ds_read_b128 v[154:157], v212 offset:224
	s_waitcnt lgkmcnt(5)
	v_mfma_f32_32x32x16_bf16 v[118:133], v[158:161], v[14:17], v[118:133]
	ds_read_b128 v[158:161], v212 offset:256
	s_waitcnt lgkmcnt(5)
	v_mfma_f32_32x32x16_bf16 v[118:133], v[162:165], v[18:21], v[118:133]
	ds_read_b128 v[162:165], v212 offset:288
	s_waitcnt lgkmcnt(5)
	v_mfma_f32_32x32x16_bf16 v[118:133], v[166:169], v[22:25], v[118:133]
	ds_read_b128 v[166:169], v212 offset:320
	s_waitcnt lgkmcnt(5)
	v_mfma_f32_32x32x16_bf16 v[118:133], v[170:173], v[26:29], v[118:133]
	ds_read_b128 v[170:173], v212 offset:352
	s_waitcnt lgkmcnt(5)
	v_mfma_f32_32x32x16_bf16 v[118:133], v[150:153], v[30:33], v[118:133]
	s_waitcnt lgkmcnt(4)
	v_mfma_f32_32x32x16_bf16 v[118:133], v[154:157], v[34:37], v[118:133]
	s_waitcnt lgkmcnt(3)
	v_mfma_f32_32x32x16_bf16 v[118:133], v[158:161], v[38:41], v[118:133]
	s_waitcnt lgkmcnt(2)
	v_mfma_f32_32x32x16_bf16 v[118:133], v[162:165], v[42:45], v[118:133]
	s_waitcnt lgkmcnt(1)
	v_mfma_f32_32x32x16_bf16 v[118:133], v[166:169], v[46:49], v[118:133]
	s_waitcnt lgkmcnt(0)
	v_mfma_f32_32x32x16_bf16 v[118:133], v[170:173], v[50:53], v[118:133]
	s_mov_b32 s47, 43
.Lfa_loop:
	ds_read_b128 v[150:153], v212 offset:23040
	ds_read_b128 v[154:157], v212 offset:23072
	ds_read_b128 v[158:161], v212 offset:23104
	ds_read_b128 v[162:165], v212 offset:23136
	ds_read_b128 v[166:169], v212 offset:23168
	ds_read_b128 v[170:173], v212 offset:23200
	s_waitcnt lgkmcnt(5)
	v_mfma_f32_32x32x16_bf16 v[134:149], v[150:153], v[6:9], 0
	ds_read_b128 v[150:153], v212 offset:23232
	ds_read_b128 v[174:177], v213 offset:0
	ds_read_b128 v[178:181], v213 offset:2560
	v_exp_f32_e32 v118, v118
	v_exp_f32_e32 v119, v119
	s_waitcnt lgkmcnt(7)
	v_mfma_f32_32x32x16_bf16 v[134:149], v[154:157], v[10:13], v[134:149]
	ds_read_b128 v[154:157], v212 offset:23264
	ds_read_b128 v[182:185], v213 offset:5120
	ds_read_b128 v[188:191], v213 offset:7680
	v_add_f32_e32 v0, v0, v118
	v_add_f32_e32 v0, v0, v119
	s_waitcnt lgkmcnt(9)
	v_mfma_f32_32x32x16_bf16 v[134:149], v[158:161], v[14:17], v[134:149]
	ds_read_b128 v[158:161], v212 offset:23296
	ds_read_b128 v[192:195], v213 offset:32
	ds_read_b128 v[196:199], v213 offset:2592
	v_exp_f32_e32 v120, v120
	v_exp_f32_e32 v121, v121
	s_waitcnt lgkmcnt(11)
	v_mfma_f32_32x32x16_bf16 v[134:149], v[162:165], v[18:21], v[134:149]
	ds_read_b128 v[162:165], v212 offset:23328
	ds_read_b128 v[200:203], v213 offset:5152
	ds_read_b128 v[204:207], v213 offset:7712
	v_add_f32_e32 v0, v0, v120
	v_add_f32_e32 v0, v0, v121
	s_waitcnt lgkmcnt(13)
	v_mfma_f32_32x32x16_bf16 v[134:149], v[166:169], v[22:25], v[134:149]
	ds_read_b128 v[166:169], v212 offset:23360
	v_exp_f32_e32 v122, v122
	v_exp_f32_e32 v123, v123
	v_add_f32_e32 v0, v0, v122
	s_waitcnt lgkmcnt(13)
	v_mfma_f32_32x32x16_bf16 v[134:149], v[170:173], v[26:29], v[134:149]
	ds_read_b128 v[170:173], v212 offset:23392
	v_add_f32_e32 v0, v0, v123
	v_exp_f32_e32 v124, v124
	v_exp_f32_e32 v125, v125
	s_waitcnt lgkmcnt(13)
	v_mfma_f32_32x32x16_bf16 v[134:149], v[150:153], v[30:33], v[134:149]
	s_waitcnt vmcnt(4)
	ds_write_b128 v244, v[208:211] offset:46080
	global_load_dwordx4 v[208:211], v248, s[56:57]
	v_add_f32_e32 v0, v0, v124
	v_add_f32_e32 v0, v0, v125
	v_cvt_pk_bf16_f32 v118, v118, v119
	s_waitcnt lgkmcnt(11)
	v_mfma_f32_32x32x16_bf16 v[134:149], v[154:157], v[34:37], v[134:149]
	s_waitcnt vmcnt(4)
	ds_write_b128 v245, v[216:219] offset:46080
	global_load_dwordx4 v[216:219], v248, s[98:99] offset:-4096
	v_cvt_pk_bf16_f32 v119, v120, v121
	v_cvt_pk_bf16_f32 v120, v122, v123
	v_cvt_pk_bf16_f32 v121, v124, v125
	s_waitcnt lgkmcnt(9)
	v_mfma_f32_32x32x16_bf16 v[134:149], v[158:161], v[38:41], v[134:149]
	s_waitcnt vmcnt(4)
	ds_write_b128 v246, v[220:223] offset:46080
	global_load_dwordx4 v[220:223], v248, s[98:99]
	v_exp_f32_e32 v126, v126
	v_exp_f32_e32 v127, v127
	v_add_f32_e32 v0, v0, v126
	s_waitcnt lgkmcnt(7)
	v_mfma_f32_32x32x16_bf16 v[134:149], v[162:165], v[42:45], v[134:149]
	s_waitcnt vmcnt(4)
	ds_write_b128 v247, v[236:239] offset:46080
	global_load_dwordx4 v[236:239], v235, s[52:53]
	v_add_f32_e32 v0, v0, v127
	v_exp_f32_e32 v128, v128
	v_exp_f32_e32 v129, v129
	s_waitcnt lgkmcnt(5)
	v_mfma_f32_32x32x16_bf16 v[134:149], v[166:169], v[46:49], v[134:149]
	s_waitcnt vmcnt(4)
	ds_write_b128 v247, v[240:243] offset:51200
	global_load_dwordx4 v[240:243], v235, s[100:101]
	v_add_f32_e32 v0, v0, v128
	v_add_f32_e32 v0, v0, v129
	v_exp_f32_e32 v130, v130
	s_waitcnt lgkmcnt(5)
	v_mfma_f32_32x32x16_bf16 v[134:149], v[170:173], v[50:53], v[134:149]
	v_exp_f32_e32 v131, v131
	v_add_f32_e32 v0, v0, v130
	v_add_f32_e32 v0, v0, v131
	v_mfma_f32_32x32x16_bf16 v[54:69], v[174:177], v[118:121], v[54:69]
	v_exp_f32_e32 v132, v132
	v_exp_f32_e32 v133, v133
	v_mfma_f32_32x32x16_bf16 v[70:85], v[178:181], v[118:121], v[70:85]
	v_add_f32_e32 v0, v0, v132
	v_add_f32_e32 v0, v0, v133
	v_mfma_f32_32x32x16_bf16 v[86:101], v[182:185], v[118:121], v[86:101]
	v_cvt_pk_bf16_f32 v126, v126, v127
	v_cvt_pk_bf16_f32 v127, v128, v129
	v_mfma_f32_32x32x16_bf16 v[102:117], v[188:191], v[118:121], v[102:117]
	v_cvt_pk_bf16_f32 v128, v130, v131
	v_cvt_pk_bf16_f32 v129, v132, v133
	s_nop 1
	v_mfma_f32_32x32x16_bf16 v[54:69], v[192:195], v[126:129], v[54:69]
	s_add_u32 s56, s56, 0x3000
	s_addc_u32 s57, s57, 0
	v_mfma_f32_32x32x16_bf16 v[70:85], v[196:199], v[126:129], v[70:85]
	s_add_u32 s98, s98, 0x3000
	s_addc_u32 s99, s99, 0
	v_mfma_f32_32x32x16_bf16 v[86:101], v[200:203], v[126:129], v[86:101]
	s_add_u32 s52, s52, 64
	s_addc_u32 s53, s53, 0
	v_mfma_f32_32x32x16_bf16 v[102:117], v[204:207], v[126:129], v[102:117]
	s_add_u32 s100, s100, 64
	s_addc_u32 s101, s101, 0
	s_waitcnt lgkmcnt(0)
	s_barrier
	ds_read_b128 v[150:153], v212 offset:46080
	ds_read_b128 v[154:157], v212 offset:46112
	ds_read_b128 v[158:161], v212 offset:46144
	ds_read_b128 v[162:165], v212 offset:46176
	ds_read_b128 v[166:169], v212 offset:46208
	ds_read_b128 v[170:173], v212 offset:46240
	s_waitcnt lgkmcnt(5)
	v_mfma_f32_32x32x16_bf16 v[118:133], v[150:153], v[6:9], 0
	ds_read_b128 v[150:153], v212 offset:46272
	ds_read_b128 v[174:177], v213 offset:23040
	ds_read_b128 v[178:181], v213 offset:25600
	v_exp_f32_e32 v134, v134
	v_exp_f32_e32 v135, v135
	s_waitcnt lgkmcnt(7)
	v_mfma_f32_32x32x16_bf16 v[118:133], v[154:157], v[10:13], v[118:133]
	ds_read_b128 v[154:157], v212 offset:46304
	ds_read_b128 v[182:185], v213 offset:28160
	ds_read_b128 v[188:191], v213 offset:30720
	v_add_f32_e32 v0, v0, v134
	v_add_f32_e32 v0, v0, v135
	s_waitcnt lgkmcnt(9)
	v_mfma_f32_32x32x16_bf16 v[118:133], v[158:161], v[14:17], v[118:133]
	ds_read_b128 v[158:161], v212 offset:46336
	ds_read_b128 v[192:195], v213 offset:23072
	ds_read_b128 v[196:199], v213 offset:25632
	v_exp_f32_e32 v136, v136
	v_exp_f32_e32 v137, v137
	s_waitcnt lgkmcnt(11)
	v_mfma_f32_32x32x16_bf16 v[118:133], v[162:165], v[18:21], v[118:133]
	ds_read_b128 v[162:165], v212 offset:46368
	ds_read_b128 v[200:203], v213 offset:28192
	ds_read_b128 v[204:207], v213 offset:30752
	v_add_f32_e32 v0, v0, v136
	v_add_f32_e32 v0, v0, v137
	s_waitcnt lgkmcnt(13)
	v_mfma_f32_32x32x16_bf16 v[118:133], v[166:169], v[22:25], v[118:133]
	ds_read_b128 v[166:169], v212 offset:46400
	v_exp_f32_e32 v138, v138
	v_exp_f32_e32 v139, v139
	v_add_f32_e32 v0, v0, v138
	s_waitcnt lgkmcnt(13)
	v_mfma_f32_32x32x16_bf16 v[118:133], v[170:173], v[26:29], v[118:133]
	ds_read_b128 v[170:173], v212 offset:46432
	v_add_f32_e32 v0, v0, v139
	v_exp_f32_e32 v140, v140
	v_exp_f32_e32 v141, v141
	s_waitcnt lgkmcnt(13)
	v_mfma_f32_32x32x16_bf16 v[118:133], v[150:153], v[30:33], v[118:133]
	s_waitcnt vmcnt(4)
	ds_write_b128 v244, v[208:211] offset:0
	global_load_dwordx4 v[208:211], v248, s[56:57]
	v_add_f32_e32 v0, v0, v140
	v_add_f32_e32 v0, v0, v141
	v_cvt_pk_bf16_f32 v134, v134, v135
	s_waitcnt lgkmcnt(11)
	v_mfma_f32_32x32x16_bf16 v[118:133], v[154:157], v[34:37], v[118:133]
	s_waitcnt vmcnt(4)
	ds_write_b128 v245, v[216:219] offset:0
	global_load_dwordx4 v[216:219], v248, s[98:99] offset:-4096
	v_cvt_pk_bf16_f32 v135, v136, v137
	v_cvt_pk_bf16_f32 v136, v138, v139
	v_cvt_pk_bf16_f32 v137, v140, v141
	s_waitcnt lgkmcnt(9)
	v_mfma_f32_32x32x16_bf16 v[118:133], v[158:161], v[38:41], v[118:133]
	s_waitcnt vmcnt(4)
	ds_write_b128 v246, v[220:223] offset:0
	global_load_dwordx4 v[220:223], v248, s[98:99]
	v_exp_f32_e32 v142, v142
	v_exp_f32_e32 v143, v143
	v_add_f32_e32 v0, v0, v142
	s_waitcnt lgkmcnt(7)
	v_mfma_f32_32x32x16_bf16 v[118:133], v[162:165], v[42:45], v[118:133]
	s_waitcnt vmcnt(4)
	ds_write_b128 v247, v[236:239] offset:0
	global_load_dwordx4 v[236:239], v235, s[52:53]
	v_add_f32_e32 v0, v0, v143
	v_exp_f32_e32 v144, v144
	v_exp_f32_e32 v145, v145
	s_waitcnt lgkmcnt(5)
	v_mfma_f32_32x32x16_bf16 v[118:133], v[166:169], v[46:49], v[118:133]
	s_waitcnt vmcnt(4)
	ds_write_b128 v247, v[240:243] offset:5120
	global_load_dwordx4 v[240:243], v235, s[100:101]
	v_add_f32_e32 v0, v0, v144
	v_add_f32_e32 v0, v0, v145
	v_exp_f32_e32 v146, v146
	s_waitcnt lgkmcnt(5)
	v_mfma_f32_32x32x16_bf16 v[118:133], v[170:173], v[50:53], v[118:133]
	v_exp_f32_e32 v147, v147
	v_add_f32_e32 v0, v0, v146
	v_add_f32_e32 v0, v0, v147
	v_mfma_f32_32x32x16_bf16 v[54:69], v[174:177], v[134:137], v[54:69]
	v_exp_f32_e32 v148, v148
	v_exp_f32_e32 v149, v149
	v_mfma_f32_32x32x16_bf16 v[70:85], v[178:181], v[134:137], v[70:85]
	v_add_f32_e32 v0, v0, v148
	v_add_f32_e32 v0, v0, v149
	v_mfma_f32_32x32x16_bf16 v[86:101], v[182:185], v[134:137], v[86:101]
	v_cvt_pk_bf16_f32 v142, v142, v143
	v_cvt_pk_bf16_f32 v143, v144, v145
	v_mfma_f32_32x32x16_bf16 v[102:117], v[188:191], v[134:137], v[102:117]
	v_cvt_pk_bf16_f32 v144, v146, v147
	v_cvt_pk_bf16_f32 v145, v148, v149
	s_nop 1
	v_mfma_f32_32x32x16_bf16 v[54:69], v[192:195], v[142:145], v[54:69]
	s_add_u32 s56, s56, 0x3000
	s_addc_u32 s57, s57, 0
	v_mfma_f32_32x32x16_bf16 v[70:85], v[196:199], v[142:145], v[70:85]
	s_add_u32 s98, s98, 0x3000
	s_addc_u32 s99, s99, 0
	v_mfma_f32_32x32x16_bf16 v[86:101], v[200:203], v[142:145], v[86:101]
	s_add_u32 s52, s52, 64
	s_addc_u32 s53, s53, 0
	v_mfma_f32_32x32x16_bf16 v[102:117], v[204:207], v[142:145], v[102:117]
	s_add_u32 s100, s100, 64
	s_addc_u32 s101, s101, 0
	s_waitcnt lgkmcnt(0)
	s_barrier
	ds_read_b128 v[150:153], v212 offset:0
	ds_read_b128 v[154:157], v212 offset:32
	ds_read_b128 v[158:161], v212 offset:64
	ds_read_b128 v[162:165], v212 offset:96
	ds_read_b128 v[166:169], v212 offset:128
	ds_read_b128 v[170:173], v212 offset:160
	s_waitcnt lgkmcnt(5)
	v_mfma_f32_32x32x16_bf16 v[134:149], v[150:153], v[6:9], 0
	ds_read_b128 v[150:153], v212 offset:192
	ds_read_b128 v[174:177], v213 offset:46080
	ds_read_b128 v[178:181], v213 offset:48640
	v_exp_f32_e32 v118, v118
	v_exp_f32_e32 v119, v119
	s_waitcnt lgkmcnt(7)
	v_mfma_f32_32x32x16_bf16 v[134:149], v[154:157], v[10:13], v[134:149]
	ds_read_b128 v[154:157], v212 offset:224
	ds_read_b128 v[182:185], v213 offset:51200
	ds_read_b128 v[188:191], v213 offset:53760
	v_add_f32_e32 v0, v0, v118
	v_add_f32_e32 v0, v0, v119
	s_waitcnt lgkmcnt(9)
	v_mfma_f32_32x32x16_bf16 v[134:149], v[158:161], v[14:17], v[134:149]
	ds_read_b128 v[158:161], v212 offset:256
	ds_read_b128 v[192:195], v213 offset:46112
	ds_read_b128 v[196:199], v213 offset:48672
	v_exp_f32_e32 v120, v120
	v_exp_f32_e32 v121, v121
	s_waitcnt lgkmcnt(11)
	v_mfma_f32_32x32x16_bf16 v[134:149], v[162:165], v[18:21], v[134:149]
	ds_read_b128 v[162:165], v212 offset:288
	ds_read_b128 v[200:203], v213 offset:51232
	ds_read_b128 v[204:207], v213 offset:53792
	v_add_f32_e32 v0, v0, v120
	v_add_f32_e32 v0, v0, v121
	s_waitcnt lgkmcnt(13)
	v_mfma_f32_32x32x16_bf16 v[134:149], v[166:169], v[22:25], v[134:149]
	ds_read_b128 v[166:169], v212 offset:320
	v_exp_f32_e32 v122, v122
	v_exp_f32_e32 v123, v123
	v_add_f32_e32 v0, v0, v122
	s_waitcnt lgkmcnt(13)
	v_mfma_f32_32x32x16_bf16 v[134:149], v[170:173], v[26:29], v[134:149]
	ds_read_b128 v[170:173], v212 offset:352
	v_add_f32_e32 v0, v0, v123
	v_exp_f32_e32 v124, v124
	v_exp_f32_e32 v125, v125
	s_waitcnt lgkmcnt(13)
	v_mfma_f32_32x32x16_bf16 v[134:149], v[150:153], v[30:33], v[134:149]
	s_waitcnt vmcnt(4)
	ds_write_b128 v244, v[208:211] offset:23040
	global_load_dwordx4 v[208:211], v248, s[56:57]
	v_add_f32_e32 v0, v0, v124
	v_add_f32_e32 v0, v0, v125
	v_cvt_pk_bf16_f32 v118, v118, v119
	s_waitcnt lgkmcnt(11)
	v_mfma_f32_32x32x16_bf16 v[134:149], v[154:157], v[34:37], v[134:149]
	s_waitcnt vmcnt(4)
	ds_write_b128 v245, v[216:219] offset:23040
	global_load_dwordx4 v[216:219], v248, s[98:99] offset:-4096
	v_cvt_pk_bf16_f32 v119, v120, v121
	v_cvt_pk_bf16_f32 v120, v122, v123
	v_cvt_pk_bf16_f32 v121, v124, v125
	s_waitcnt lgkmcnt(9)
	v_mfma_f32_32x32x16_bf16 v[134:149], v[158:161], v[38:41], v[134:149]
	s_waitcnt vmcnt(4)
	ds_write_b128 v246, v[220:223] offset:23040
	global_load_dwordx4 v[220:223], v248, s[98:99]
	v_exp_f32_e32 v126, v126
	v_exp_f32_e32 v127, v127
	v_add_f32_e32 v0, v0, v126
	s_waitcnt lgkmcnt(7)
	v_mfma_f32_32x32x16_bf16 v[134:149], v[162:165], v[42:45], v[134:149]
	s_waitcnt vmcnt(4)
	ds_write_b128 v247, v[236:239] offset:23040
	global_load_dwordx4 v[236:239], v235, s[52:53]
	v_add_f32_e32 v0, v0, v127
	v_exp_f32_e32 v128, v128
	v_exp_f32_e32 v129, v129
	s_waitcnt lgkmcnt(5)
	v_mfma_f32_32x32x16_bf16 v[134:149], v[166:169], v[46:49], v[134:149]
	s_waitcnt vmcnt(4)
	ds_write_b128 v247, v[240:243] offset:28160
	global_load_dwordx4 v[240:243], v235, s[100:101]
	v_add_f32_e32 v0, v0, v128
	v_add_f32_e32 v0, v0, v129
	v_exp_f32_e32 v130, v130
	s_waitcnt lgkmcnt(5)
	v_mfma_f32_32x32x16_bf16 v[134:149], v[170:173], v[50:53], v[134:149]
	v_exp_f32_e32 v131, v131
	v_add_f32_e32 v0, v0, v130
	v_add_f32_e32 v0, v0, v131
	v_mfma_f32_32x32x16_bf16 v[54:69], v[174:177], v[118:121], v[54:69]
	v_exp_f32_e32 v132, v132
	v_exp_f32_e32 v133, v133
	v_mfma_f32_32x32x16_bf16 v[70:85], v[178:181], v[118:121], v[70:85]
	v_add_f32_e32 v0, v0, v132
	v_add_f32_e32 v0, v0, v133
	v_mfma_f32_32x32x16_bf16 v[86:101], v[182:185], v[118:121], v[86:101]
	v_cvt_pk_bf16_f32 v126, v126, v127
	v_cvt_pk_bf16_f32 v127, v128, v129
	v_mfma_f32_32x32x16_bf16 v[102:117], v[188:191], v[118:121], v[102:117]
	v_cvt_pk_bf16_f32 v128, v130, v131
	v_cvt_pk_bf16_f32 v129, v132, v133
	s_nop 1
	v_mfma_f32_32x32x16_bf16 v[54:69], v[192:195], v[126:129], v[54:69]
	s_add_u32 s56, s56, 0x3000
	s_addc_u32 s57, s57, 0
	v_mfma_f32_32x32x16_bf16 v[70:85], v[196:199], v[126:129], v[70:85]
	s_add_u32 s98, s98, 0x3000
	s_addc_u32 s99, s99, 0
	v_mfma_f32_32x32x16_bf16 v[86:101], v[200:203], v[126:129], v[86:101]
	s_add_u32 s52, s52, 64
	s_addc_u32 s53, s53, 0
	v_mfma_f32_32x32x16_bf16 v[102:117], v[204:207], v[126:129], v[102:117]
	s_add_u32 s100, s100, 64
	s_addc_u32 s101, s101, 0
	s_waitcnt lgkmcnt(0)
	s_barrier
	ds_read_b128 v[150:153], v212 offset:23040
	ds_read_b128 v[154:157], v212 offset:23072
	ds_read_b128 v[158:161], v212 offset:23104
	ds_read_b128 v[162:165], v212 offset:23136
	ds_read_b128 v[166:169], v212 offset:23168
	ds_read_b128 v[170:173], v212 offset:23200
	s_waitcnt lgkmcnt(5)
	v_mfma_f32_32x32x16_bf16 v[118:133], v[150:153], v[6:9], 0
	ds_read_b128 v[150:153], v212 offset:23232
	ds_read_b128 v[174:177], v213 offset:0
	ds_read_b128 v[178:181], v213 offset:2560
	v_exp_f32_e32 v134, v134
	v_exp_f32_e32 v135, v135
	s_waitcnt lgkmcnt(7)
	v_mfma_f32_32x32x16_bf16 v[118:133], v[154:157], v[10:13], v[118:133]
	ds_read_b128 v[154:157], v212 offset:23264
	ds_read_b128 v[182:185], v213 offset:5120
	ds_read_b128 v[188:191], v213 offset:7680
	v_add_f32_e32 v0, v0, v134
	v_add_f32_e32 v0, v0, v135
	s_waitcnt lgkmcnt(9)
	v_mfma_f32_32x32x16_bf16 v[118:133], v[158:161], v[14:17], v[118:133]
	ds_read_b128 v[158:161], v212 offset:23296
	ds_read_b128 v[192:195], v213 offset:32
	ds_read_b128 v[196:199], v213 offset:2592
	v_exp_f32_e32 v136, v136
	v_exp_f32_e32 v137, v137
	s_waitcnt lgkmcnt(11)
	v_mfma_f32_32x32x16_bf16 v[118:133], v[162:165], v[18:21], v[118:133]
	ds_read_b128 v[162:165], v212 offset:23328
	ds_read_b128 v[200:203], v213 offset:5152
	ds_read_b128 v[204:207], v213 offset:7712
	v_add_f32_e32 v0, v0, v136
	v_add_f32_e32 v0, v0, v137
	s_waitcnt lgkmcnt(13)
	v_mfma_f32_32x32x16_bf16 v[118:133], v[166:169], v[22:25], v[118:133]
	ds_read_b128 v[166:169], v212 offset:23360
	v_exp_f32_e32 v138, v138
	v_exp_f32_e32 v139, v139
	v_add_f32_e32 v0, v0, v138
	s_waitcnt lgkmcnt(13)
	v_mfma_f32_32x32x16_bf16 v[118:133], v[170:173], v[26:29], v[118:133]
	ds_read_b128 v[170:173], v212 offset:23392
	v_add_f32_e32 v0, v0, v139
	v_exp_f32_e32 v140, v140
	v_exp_f32_e32 v141, v141
	s_waitcnt lgkmcnt(13)
	v_mfma_f32_32x32x16_bf16 v[118:133], v[150:153], v[30:33], v[118:133]
	s_waitcnt vmcnt(4)
	ds_write_b128 v244, v[208:211] offset:46080
	global_load_dwordx4 v[208:211], v248, s[56:57]
	v_add_f32_e32 v0, v0, v140
	v_add_f32_e32 v0, v0, v141
	v_cvt_pk_bf16_f32 v134, v134, v135
	s_waitcnt lgkmcnt(11)
	v_mfma_f32_32x32x16_bf16 v[118:133], v[154:157], v[34:37], v[118:133]
	s_waitcnt vmcnt(4)
	ds_write_b128 v245, v[216:219] offset:46080
	global_load_dwordx4 v[216:219], v248, s[98:99] offset:-4096
	v_cvt_pk_bf16_f32 v135, v136, v137
	v_cvt_pk_bf16_f32 v136, v138, v139
	v_cvt_pk_bf16_f32 v137, v140, v141
	s_waitcnt lgkmcnt(9)
	v_mfma_f32_32x32x16_bf16 v[118:133], v[158:161], v[38:41], v[118:133]
	s_waitcnt vmcnt(4)
	ds_write_b128 v246, v[220:223] offset:46080
	global_load_dwordx4 v[220:223], v248, s[98:99]
	v_exp_f32_e32 v142, v142
	v_exp_f32_e32 v143, v143
	v_add_f32_e32 v0, v0, v142
	s_waitcnt lgkmcnt(7)
	v_mfma_f32_32x32x16_bf16 v[118:133], v[162:165], v[42:45], v[118:133]
	s_waitcnt vmcnt(4)
	ds_write_b128 v247, v[236:239] offset:46080
	global_load_dwordx4 v[236:239], v235, s[52:53]
	v_add_f32_e32 v0, v0, v143
	v_exp_f32_e32 v144, v144
	v_exp_f32_e32 v145, v145
	s_waitcnt lgkmcnt(5)
	v_mfma_f32_32x32x16_bf16 v[118:133], v[166:169], v[46:49], v[118:133]
	s_waitcnt vmcnt(4)
	ds_write_b128 v247, v[240:243] offset:51200
	global_load_dwordx4 v[240:243], v235, s[100:101]
	v_add_f32_e32 v0, v0, v144
	v_add_f32_e32 v0, v0, v145
	v_exp_f32_e32 v146, v146
	s_waitcnt lgkmcnt(5)
	v_mfma_f32_32x32x16_bf16 v[118:133], v[170:173], v[50:53], v[118:133]
	v_exp_f32_e32 v147, v147
	v_add_f32_e32 v0, v0, v146
	v_add_f32_e32 v0, v0, v147
	v_mfma_f32_32x32x16_bf16 v[54:69], v[174:177], v[134:137], v[54:69]
	v_exp_f32_e32 v148, v148
	v_exp_f32_e32 v149, v149
	v_mfma_f32_32x32x16_bf16 v[70:85], v[178:181], v[134:137], v[70:85]
	v_add_f32_e32 v0, v0, v148
	v_add_f32_e32 v0, v0, v149
	v_mfma_f32_32x32x16_bf16 v[86:101], v[182:185], v[134:137], v[86:101]
	v_cvt_pk_bf16_f32 v142, v142, v143
	v_cvt_pk_bf16_f32 v143, v144, v145
	v_mfma_f32_32x32x16_bf16 v[102:117], v[188:191], v[134:137], v[102:117]
	v_cvt_pk_bf16_f32 v144, v146, v147
	v_cvt_pk_bf16_f32 v145, v148, v149
	s_nop 1
	v_mfma_f32_32x32x16_bf16 v[54:69], v[192:195], v[142:145], v[54:69]
	s_add_u32 s56, s56, 0x3000
	s_addc_u32 s57, s57, 0
	v_mfma_f32_32x32x16_bf16 v[70:85], v[196:199], v[142:145], v[70:85]
	s_add_u32 s98, s98, 0x3000
	s_addc_u32 s99, s99, 0
	v_mfma_f32_32x32x16_bf16 v[86:101], v[200:203], v[142:145], v[86:101]
	s_add_u32 s52, s52, 64
	s_addc_u32 s53, s53, 0
	v_mfma_f32_32x32x16_bf16 v[102:117], v[204:207], v[142:145], v[102:117]
	s_add_u32 s100, s100, 64
	s_addc_u32 s101, s101, 0
	s_waitcnt lgkmcnt(0)
	s_barrier
	ds_read_b128 v[150:153], v212 offset:46080
	ds_read_b128 v[154:157], v212 offset:46112
	ds_read_b128 v[158:161], v212 offset:46144
	ds_read_b128 v[162:165], v212 offset:46176
	ds_read_b128 v[166:169], v212 offset:46208
	ds_read_b128 v[170:173], v212 offset:46240
	s_waitcnt lgkmcnt(5)
	v_mfma_f32_32x32x16_bf16 v[134:149], v[150:153], v[6:9], 0
	ds_read_b128 v[150:153], v212 offset:46272
	ds_read_b128 v[174:177], v213 offset:23040
	ds_read_b128 v[178:181], v213 offset:25600
	v_exp_f32_e32 v118, v118
	v_exp_f32_e32 v119, v119
	s_waitcnt lgkmcnt(7)
	v_mfma_f32_32x32x16_bf16 v[134:149], v[154:157], v[10:13], v[134:149]
	ds_read_b128 v[154:157], v212 offset:46304
	ds_read_b128 v[182:185], v213 offset:28160
	ds_read_b128 v[188:191], v213 offset:30720
	v_add_f32_e32 v0, v0, v118
	v_add_f32_e32 v0, v0, v119
	s_waitcnt lgkmcnt(9)
	v_mfma_f32_32x32x16_bf16 v[134:149], v[158:161], v[14:17], v[134:149]
	ds_read_b128 v[158:161], v212 offset:46336
	ds_read_b128 v[192:195], v213 offset:23072
	ds_read_b128 v[196:199], v213 offset:25632
	v_exp_f32_e32 v120, v120
	v_exp_f32_e32 v121, v121
	s_waitcnt lgkmcnt(11)
	v_mfma_f32_32x32x16_bf16 v[134:149], v[162:165], v[18:21], v[134:149]
	ds_read_b128 v[162:165], v212 offset:46368
	ds_read_b128 v[200:203], v213 offset:28192
	ds_read_b128 v[204:207], v213 offset:30752
	v_add_f32_e32 v0, v0, v120
	v_add_f32_e32 v0, v0, v121
	s_waitcnt lgkmcnt(13)
	v_mfma_f32_32x32x16_bf16 v[134:149], v[166:169], v[22:25], v[134:149]
	ds_read_b128 v[166:169], v212 offset:46400
	v_exp_f32_e32 v122, v122
	v_exp_f32_e32 v123, v123
	v_add_f32_e32 v0, v0, v122
	s_waitcnt lgkmcnt(13)
	v_mfma_f32_32x32x16_bf16 v[134:149], v[170:173], v[26:29], v[134:149]
	ds_read_b128 v[170:173], v212 offset:46432
	v_add_f32_e32 v0, v0, v123
	v_exp_f32_e32 v124, v124
	v_exp_f32_e32 v125, v125
	s_waitcnt lgkmcnt(13)
	v_mfma_f32_32x32x16_bf16 v[134:149], v[150:153], v[30:33], v[134:149]
	s_waitcnt vmcnt(4)
	ds_write_b128 v244, v[208:211] offset:0
	global_load_dwordx4 v[208:211], v248, s[56:57]
	v_add_f32_e32 v0, v0, v124
	v_add_f32_e32 v0, v0, v125
	v_cvt_pk_bf16_f32 v118, v118, v119
	s_waitcnt lgkmcnt(11)
	v_mfma_f32_32x32x16_bf16 v[134:149], v[154:157], v[34:37], v[134:149]
	s_waitcnt vmcnt(4)
	ds_write_b128 v245, v[216:219] offset:0
	global_load_dwordx4 v[216:219], v248, s[98:99] offset:-4096
	v_cvt_pk_bf16_f32 v119, v120, v121
	v_cvt_pk_bf16_f32 v120, v122, v123
	v_cvt_pk_bf16_f32 v121, v124, v125
	s_waitcnt lgkmcnt(9)
	v_mfma_f32_32x32x16_bf16 v[134:149], v[158:161], v[38:41], v[134:149]
	s_waitcnt vmcnt(4)
	ds_write_b128 v246, v[220:223] offset:0
	global_load_dwordx4 v[220:223], v248, s[98:99]
	v_exp_f32_e32 v126, v126
	v_exp_f32_e32 v127, v127
	v_add_f32_e32 v0, v0, v126
	s_waitcnt lgkmcnt(7)
	v_mfma_f32_32x32x16_bf16 v[134:149], v[162:165], v[42:45], v[134:149]
	s_waitcnt vmcnt(4)
	ds_write_b128 v247, v[236:239] offset:0
	global_load_dwordx4 v[236:239], v235, s[52:53]
	v_add_f32_e32 v0, v0, v127
	v_exp_f32_e32 v128, v128
	v_exp_f32_e32 v129, v129
	s_waitcnt lgkmcnt(5)
	v_mfma_f32_32x32x16_bf16 v[134:149], v[166:169], v[46:49], v[134:149]
	s_waitcnt vmcnt(4)
	ds_write_b128 v247, v[240:243] offset:5120
	global_load_dwordx4 v[240:243], v235, s[100:101]
	v_add_f32_e32 v0, v0, v128
	v_add_f32_e32 v0, v0, v129
	v_exp_f32_e32 v130, v130
	s_waitcnt lgkmcnt(5)
	v_mfma_f32_32x32x16_bf16 v[134:149], v[170:173], v[50:53], v[134:149]
	v_exp_f32_e32 v131, v131
	v_add_f32_e32 v0, v0, v130
	v_add_f32_e32 v0, v0, v131
	v_mfma_f32_32x32x16_bf16 v[54:69], v[174:177], v[118:121], v[54:69]
	v_exp_f32_e32 v132, v132
	v_exp_f32_e32 v133, v133
	v_mfma_f32_32x32x16_bf16 v[70:85], v[178:181], v[118:121], v[70:85]
	v_add_f32_e32 v0, v0, v132
	v_add_f32_e32 v0, v0, v133
	v_mfma_f32_32x32x16_bf16 v[86:101], v[182:185], v[118:121], v[86:101]
	v_cvt_pk_bf16_f32 v126, v126, v127
	v_cvt_pk_bf16_f32 v127, v128, v129
	v_mfma_f32_32x32x16_bf16 v[102:117], v[188:191], v[118:121], v[102:117]
	v_cvt_pk_bf16_f32 v128, v130, v131
	v_cvt_pk_bf16_f32 v129, v132, v133
	s_nop 1
	v_mfma_f32_32x32x16_bf16 v[54:69], v[192:195], v[126:129], v[54:69]
	s_add_u32 s56, s56, 0x3000
	s_addc_u32 s57, s57, 0
	v_mfma_f32_32x32x16_bf16 v[70:85], v[196:199], v[126:129], v[70:85]
	s_add_u32 s98, s98, 0x3000
	s_addc_u32 s99, s99, 0
	v_mfma_f32_32x32x16_bf16 v[86:101], v[200:203], v[126:129], v[86:101]
	s_add_u32 s52, s52, 64
	s_addc_u32 s53, s53, 0
	v_mfma_f32_32x32x16_bf16 v[102:117], v[204:207], v[126:129], v[102:117]
	s_add_u32 s100, s100, 64
	s_addc_u32 s101, s101, 0
	s_waitcnt lgkmcnt(0)
	s_barrier
	ds_read_b128 v[150:153], v212 offset:0
	ds_read_b128 v[154:157], v212 offset:32
	ds_read_b128 v[158:161], v212 offset:64
	ds_read_b128 v[162:165], v212 offset:96
	ds_read_b128 v[166:169], v212 offset:128
	ds_read_b128 v[170:173], v212 offset:160
	s_waitcnt lgkmcnt(5)
	v_mfma_f32_32x32x16_bf16 v[118:133], v[150:153], v[6:9], 0
	ds_read_b128 v[150:153], v212 offset:192
	ds_read_b128 v[174:177], v213 offset:46080
	ds_read_b128 v[178:181], v213 offset:48640
	v_exp_f32_e32 v134, v134
	v_exp_f32_e32 v135, v135
	s_waitcnt lgkmcnt(7)
	v_mfma_f32_32x32x16_bf16 v[118:133], v[154:157], v[10:13], v[118:133]
	ds_read_b128 v[154:157], v212 offset:224
	ds_read_b128 v[182:185], v213 offset:51200
	ds_read_b128 v[188:191], v213 offset:53760
	v_add_f32_e32 v0, v0, v134
	v_add_f32_e32 v0, v0, v135
	s_waitcnt lgkmcnt(9)
	v_mfma_f32_32x32x16_bf16 v[118:133], v[158:161], v[14:17], v[118:133]
	ds_read_b128 v[158:161], v212 offset:256
	ds_read_b128 v[192:195], v213 offset:46112
	ds_read_b128 v[196:199], v213 offset:48672
	v_exp_f32_e32 v136, v136
	v_exp_f32_e32 v137, v137
	s_waitcnt lgkmcnt(11)
	v_mfma_f32_32x32x16_bf16 v[118:133], v[162:165], v[18:21], v[118:133]
	ds_read_b128 v[162:165], v212 offset:288
	ds_read_b128 v[200:203], v213 offset:51232
	ds_read_b128 v[204:207], v213 offset:53792
	v_add_f32_e32 v0, v0, v136
	v_add_f32_e32 v0, v0, v137
	s_waitcnt lgkmcnt(13)
	v_mfma_f32_32x32x16_bf16 v[118:133], v[166:169], v[22:25], v[118:133]
	ds_read_b128 v[166:169], v212 offset:320
	v_exp_f32_e32 v138, v138
	v_exp_f32_e32 v139, v139
	v_add_f32_e32 v0, v0, v138
	s_waitcnt lgkmcnt(13)
	v_mfma_f32_32x32x16_bf16 v[118:133], v[170:173], v[26:29], v[118:133]
	ds_read_b128 v[170:173], v212 offset:352
	v_add_f32_e32 v0, v0, v139
	v_exp_f32_e32 v140, v140
	v_exp_f32_e32 v141, v141
	s_waitcnt lgkmcnt(13)
	v_mfma_f32_32x32x16_bf16 v[118:133], v[150:153], v[30:33], v[118:133]
	s_waitcnt vmcnt(4)
	ds_write_b128 v244, v[208:211] offset:23040
	global_load_dwordx4 v[208:211], v248, s[56:57]
	v_add_f32_e32 v0, v0, v140
	v_add_f32_e32 v0, v0, v141
	v_cvt_pk_bf16_f32 v134, v134, v135
	s_waitcnt lgkmcnt(11)
	v_mfma_f32_32x32x16_bf16 v[118:133], v[154:157], v[34:37], v[118:133]
	s_waitcnt vmcnt(4)
	ds_write_b128 v245, v[216:219] offset:23040
	global_load_dwordx4 v[216:219], v248, s[98:99] offset:-4096
	v_cvt_pk_bf16_f32 v135, v136, v137
	v_cvt_pk_bf16_f32 v136, v138, v139
	v_cvt_pk_bf16_f32 v137, v140, v141
	s_waitcnt lgkmcnt(9)
	v_mfma_f32_32x32x16_bf16 v[118:133], v[158:161], v[38:41], v[118:133]
	s_waitcnt vmcnt(4)
	ds_write_b128 v246, v[220:223] offset:23040
	global_load_dwordx4 v[220:223], v248, s[98:99]
	v_exp_f32_e32 v142, v142
	v_exp_f32_e32 v143, v143
	v_add_f32_e32 v0, v0, v142
	s_waitcnt lgkmcnt(7)
	v_mfma_f32_32x32x16_bf16 v[118:133], v[162:165], v[42:45], v[118:133]
	s_waitcnt vmcnt(4)
	ds_write_b128 v247, v[236:239] offset:23040
	global_load_dwordx4 v[236:239], v235, s[52:53]
	v_add_f32_e32 v0, v0, v143
	v_exp_f32_e32 v144, v144
	v_exp_f32_e32 v145, v145
	s_waitcnt lgkmcnt(5)
	v_mfma_f32_32x32x16_bf16 v[118:133], v[166:169], v[46:49], v[118:133]
	s_waitcnt vmcnt(4)
	ds_write_b128 v247, v[240:243] offset:28160
	global_load_dwordx4 v[240:243], v235, s[100:101]
	v_add_f32_e32 v0, v0, v144
	v_add_f32_e32 v0, v0, v145
	v_exp_f32_e32 v146, v146
	s_waitcnt lgkmcnt(5)
	v_mfma_f32_32x32x16_bf16 v[118:133], v[170:173], v[50:53], v[118:133]
	v_exp_f32_e32 v147, v147
	v_add_f32_e32 v0, v0, v146
	v_add_f32_e32 v0, v0, v147
	v_mfma_f32_32x32x16_bf16 v[54:69], v[174:177], v[134:137], v[54:69]
	v_exp_f32_e32 v148, v148
	v_exp_f32_e32 v149, v149
	v_mfma_f32_32x32x16_bf16 v[70:85], v[178:181], v[134:137], v[70:85]
	v_add_f32_e32 v0, v0, v148
	v_add_f32_e32 v0, v0, v149
	v_mfma_f32_32x32x16_bf16 v[86:101], v[182:185], v[134:137], v[86:101]
	v_cvt_pk_bf16_f32 v142, v142, v143
	v_cvt_pk_bf16_f32 v143, v144, v145
	v_mfma_f32_32x32x16_bf16 v[102:117], v[188:191], v[134:137], v[102:117]
	v_cvt_pk_bf16_f32 v144, v146, v147
	v_cvt_pk_bf16_f32 v145, v148, v149
	s_nop 1
	v_mfma_f32_32x32x16_bf16 v[54:69], v[192:195], v[142:145], v[54:69]
	s_add_u32 s56, s56, 0x3000
	s_addc_u32 s57, s57, 0
	v_mfma_f32_32x32x16_bf16 v[70:85], v[196:199], v[142:145], v[70:85]
	s_add_u32 s98, s98, 0x3000
	s_addc_u32 s99, s99, 0
	v_mfma_f32_32x32x16_bf16 v[86:101], v[200:203], v[142:145], v[86:101]
	s_add_u32 s52, s52, 64
	s_addc_u32 s53, s53, 0
	v_mfma_f32_32x32x16_bf16 v[102:117], v[204:207], v[142:145], v[102:117]
	s_add_u32 s100, s100, 64
	s_addc_u32 s101, s101, 0
	s_waitcnt lgkmcnt(0)
	s_barrier
	s_sub_i32 s47, s47, 1
	s_cmp_lg_u32 s47, 0
	s_cbranch_scc1 .Lfa_loop
	ds_read_b128 v[150:153], v212 offset:23040
	ds_read_b128 v[154:157], v212 offset:23072
	ds_read_b128 v[158:161], v212 offset:23104
	ds_read_b128 v[162:165], v212 offset:23136
	ds_read_b128 v[166:169], v212 offset:23168
	ds_read_b128 v[170:173], v212 offset:23200
	s_waitcnt lgkmcnt(5)
	v_mfma_f32_32x32x16_bf16 v[134:149], v[150:153], v[6:9], 0
	ds_read_b128 v[150:153], v212 offset:23232
	ds_read_b128 v[174:177], v213 offset:0
	ds_read_b128 v[178:181], v213 offset:2560
	v_exp_f32_e32 v118, v118
	v_exp_f32_e32 v119, v119
	s_waitcnt lgkmcnt(7)
	v_mfma_f32_32x32x16_bf16 v[134:149], v[154:157], v[10:13], v[134:149]
	ds_read_b128 v[154:157], v212 offset:23264
	ds_read_b128 v[182:185], v213 offset:5120
	ds_read_b128 v[188:191], v213 offset:7680
	v_add_f32_e32 v0, v0, v118
	v_add_f32_e32 v0, v0, v119
	s_waitcnt lgkmcnt(9)
	v_mfma_f32_32x32x16_bf16 v[134:149], v[158:161], v[14:17], v[134:149]
	ds_read_b128 v[158:161], v212 offset:23296
	ds_read_b128 v[192:195], v213 offset:32
	ds_read_b128 v[196:199], v213 offset:2592
	v_exp_f32_e32 v120, v120
	v_exp_f32_e32 v121, v121
	s_waitcnt lgkmcnt(11)
	v_mfma_f32_32x32x16_bf16 v[134:149], v[162:165], v[18:21], v[134:149]
	ds_read_b128 v[162:165], v212 offset:23328
	ds_read_b128 v[200:203], v213 offset:5152
	ds_read_b128 v[204:207], v213 offset:7712
	v_add_f32_e32 v0, v0, v120
	v_add_f32_e32 v0, v0, v121
	s_waitcnt lgkmcnt(13)
	v_mfma_f32_32x32x16_bf16 v[134:149], v[166:169], v[22:25], v[134:149]
	ds_read_b128 v[166:169], v212 offset:23360
	v_exp_f32_e32 v122, v122
	v_exp_f32_e32 v123, v123
	v_add_f32_e32 v0, v0, v122
	s_waitcnt lgkmcnt(13)
	v_mfma_f32_32x32x16_bf16 v[134:149], v[170:173], v[26:29], v[134:149]
	ds_read_b128 v[170:173], v212 offset:23392
	v_add_f32_e32 v0, v0, v123
	v_exp_f32_e32 v124, v124
	v_exp_f32_e32 v125, v125
	s_waitcnt lgkmcnt(13)
	v_mfma_f32_32x32x16_bf16 v[134:149], v[150:153], v[30:33], v[134:149]
	s_waitcnt vmcnt(4)
	ds_write_b128 v244, v[208:211] offset:46080
	global_load_dwordx4 v[208:211], v248, s[56:57]
	v_add_f32_e32 v0, v0, v124
	v_add_f32_e32 v0, v0, v125
	v_cvt_pk_bf16_f32 v118, v118, v119
	s_waitcnt lgkmcnt(11)
	v_mfma_f32_32x32x16_bf16 v[134:149], v[154:157], v[34:37], v[134:149]
	s_waitcnt vmcnt(4)
	ds_write_b128 v245, v[216:219] offset:46080
	global_load_dwordx4 v[216:219], v248, s[98:99] offset:-4096
	v_cvt_pk_bf16_f32 v119, v120, v121
	v_cvt_pk_bf16_f32 v120, v122, v123
	v_cvt_pk_bf16_f32 v121, v124, v125
	s_waitcnt lgkmcnt(9)
	v_mfma_f32_32x32x16_bf16 v[134:149], v[158:161], v[38:41], v[134:149]
	s_waitcnt vmcnt(4)
	ds_write_b128 v246, v[220:223] offset:46080
	global_load_dwordx4 v[220:223], v248, s[98:99]
	v_exp_f32_e32 v126, v126
	v_exp_f32_e32 v127, v127
	v_add_f32_e32 v0, v0, v126
	s_waitcnt lgkmcnt(7)
	v_mfma_f32_32x32x16_bf16 v[134:149], v[162:165], v[42:45], v[134:149]
	s_waitcnt vmcnt(4)
	ds_write_b128 v247, v[236:239] offset:46080
	global_load_dwordx4 v[236:239], v235, s[52:53]
	v_add_f32_e32 v0, v0, v127
	v_exp_f32_e32 v128, v128
	v_exp_f32_e32 v129, v129
	s_waitcnt lgkmcnt(5)
	v_mfma_f32_32x32x16_bf16 v[134:149], v[166:169], v[46:49], v[134:149]
	s_waitcnt vmcnt(4)
	ds_write_b128 v247, v[240:243] offset:51200
	global_load_dwordx4 v[240:243], v235, s[100:101]
	v_add_f32_e32 v0, v0, v128
	v_add_f32_e32 v0, v0, v129
	v_exp_f32_e32 v130, v130
	s_waitcnt lgkmcnt(5)
	v_mfma_f32_32x32x16_bf16 v[134:149], v[170:173], v[50:53], v[134:149]
	v_exp_f32_e32 v131, v131
	v_add_f32_e32 v0, v0, v130
	v_add_f32_e32 v0, v0, v131
	v_mfma_f32_32x32x16_bf16 v[54:69], v[174:177], v[118:121], v[54:69]
	v_exp_f32_e32 v132, v132
	v_exp_f32_e32 v133, v133
	v_mfma_f32_32x32x16_bf16 v[70:85], v[178:181], v[118:121], v[70:85]
	v_add_f32_e32 v0, v0, v132
	v_add_f32_e32 v0, v0, v133
	v_mfma_f32_32x32x16_bf16 v[86:101], v[182:185], v[118:121], v[86:101]
	v_cvt_pk_bf16_f32 v126, v126, v127
	v_cvt_pk_bf16_f32 v127, v128, v129
	v_mfma_f32_32x32x16_bf16 v[102:117], v[188:191], v[118:121], v[102:117]
	v_cvt_pk_bf16_f32 v128, v130, v131
	v_cvt_pk_bf16_f32 v129, v132, v133
	s_nop 1
	v_mfma_f32_32x32x16_bf16 v[54:69], v[192:195], v[126:129], v[54:69]
	s_add_u32 s56, s56, 0x3000
	s_addc_u32 s57, s57, 0
	v_mfma_f32_32x32x16_bf16 v[70:85], v[196:199], v[126:129], v[70:85]
	s_add_u32 s98, s98, 0x3000
	s_addc_u32 s99, s99, 0
	v_mfma_f32_32x32x16_bf16 v[86:101], v[200:203], v[126:129], v[86:101]
	s_add_u32 s52, s52, 64
	s_addc_u32 s53, s53, 0
	v_mfma_f32_32x32x16_bf16 v[102:117], v[204:207], v[126:129], v[102:117]
	s_add_u32 s100, s100, 64
	s_addc_u32 s101, s101, 0
	s_waitcnt lgkmcnt(0)
	s_barrier
	ds_read_b128 v[150:153], v212 offset:46080
	ds_read_b128 v[154:157], v212 offset:46112
	ds_read_b128 v[158:161], v212 offset:46144
	ds_read_b128 v[162:165], v212 offset:46176
	ds_read_b128 v[166:169], v212 offset:46208
	ds_read_b128 v[170:173], v212 offset:46240
	s_waitcnt lgkmcnt(5)
	v_mfma_f32_32x32x16_bf16 v[118:133], v[150:153], v[6:9], 0
	ds_read_b128 v[150:153], v212 offset:46272
	ds_read_b128 v[174:177], v213 offset:23040
	ds_read_b128 v[178:181], v213 offset:25600
	v_exp_f32_e32 v134, v134
	v_exp_f32_e32 v135, v135
	s_waitcnt lgkmcnt(7)
	v_mfma_f32_32x32x16_bf16 v[118:133], v[154:157], v[10:13], v[118:133]
	ds_read_b128 v[154:157], v212 offset:46304
	ds_read_b128 v[182:185], v213 offset:28160
	ds_read_b128 v[188:191], v213 offset:30720
	v_add_f32_e32 v0, v0, v134
	v_add_f32_e32 v0, v0, v135
	s_waitcnt lgkmcnt(9)
	v_mfma_f32_32x32x16_bf16 v[118:133], v[158:161], v[14:17], v[118:133]
	ds_read_b128 v[158:161], v212 offset:46336
	ds_read_b128 v[192:195], v213 offset:23072
	ds_read_b128 v[196:199], v213 offset:25632
	v_exp_f32_e32 v136, v136
	v_exp_f32_e32 v137, v137
	s_waitcnt lgkmcnt(11)
	v_mfma_f32_32x32x16_bf16 v[118:133], v[162:165], v[18:21], v[118:133]
	ds_read_b128 v[162:165], v212 offset:46368
	ds_read_b128 v[200:203], v213 offset:28192
	ds_read_b128 v[204:207], v213 offset:30752
	v_add_f32_e32 v0, v0, v136
	v_add_f32_e32 v0, v0, v137
	s_waitcnt lgkmcnt(13)
	v_mfma_f32_32x32x16_bf16 v[118:133], v[166:169], v[22:25], v[118:133]
	ds_read_b128 v[166:169], v212 offset:46400
	v_exp_f32_e32 v138, v138
	v_exp_f32_e32 v139, v139
	v_add_f32_e32 v0, v0, v138
	s_waitcnt lgkmcnt(13)
	v_mfma_f32_32x32x16_bf16 v[118:133], v[170:173], v[26:29], v[118:133]
	ds_read_b128 v[170:173], v212 offset:46432
	v_add_f32_e32 v0, v0, v139
	v_exp_f32_e32 v140, v140
	v_exp_f32_e32 v141, v141
	s_waitcnt lgkmcnt(13)
	v_mfma_f32_32x32x16_bf16 v[118:133], v[150:153], v[30:33], v[118:133]
	s_waitcnt vmcnt(4)
	ds_write_b128 v244, v[208:211] offset:0
	global_load_dwordx4 v[208:211], v248, s[56:57]
	v_add_f32_e32 v0, v0, v140
	v_add_f32_e32 v0, v0, v141
	v_cvt_pk_bf16_f32 v134, v134, v135
	s_waitcnt lgkmcnt(11)
	v_mfma_f32_32x32x16_bf16 v[118:133], v[154:157], v[34:37], v[118:133]
	s_waitcnt vmcnt(4)
	ds_write_b128 v245, v[216:219] offset:0
	global_load_dwordx4 v[216:219], v248, s[98:99] offset:-4096
	v_cvt_pk_bf16_f32 v135, v136, v137
	v_cvt_pk_bf16_f32 v136, v138, v139
	v_cvt_pk_bf16_f32 v137, v140, v141
	s_waitcnt lgkmcnt(9)
	v_mfma_f32_32x32x16_bf16 v[118:133], v[158:161], v[38:41], v[118:133]
	s_waitcnt vmcnt(4)
	ds_write_b128 v246, v[220:223] offset:0
	global_load_dwordx4 v[220:223], v248, s[98:99]
	v_exp_f32_e32 v142, v142
	v_exp_f32_e32 v143, v143
	v_add_f32_e32 v0, v0, v142
	s_waitcnt lgkmcnt(7)
	v_mfma_f32_32x32x16_bf16 v[118:133], v[162:165], v[42:45], v[118:133]
	s_waitcnt vmcnt(4)
	ds_write_b128 v247, v[236:239] offset:0
	global_load_dwordx4 v[236:239], v235, s[52:53]
	v_add_f32_e32 v0, v0, v143
	v_exp_f32_e32 v144, v144
	v_exp_f32_e32 v145, v145
	s_waitcnt lgkmcnt(5)
	v_mfma_f32_32x32x16_bf16 v[118:133], v[166:169], v[46:49], v[118:133]
	s_waitcnt vmcnt(4)
	ds_write_b128 v247, v[240:243] offset:5120
	global_load_dwordx4 v[240:243], v235, s[100:101]
	v_add_f32_e32 v0, v0, v144
	v_add_f32_e32 v0, v0, v145
	v_exp_f32_e32 v146, v146
	s_waitcnt lgkmcnt(5)
	v_mfma_f32_32x32x16_bf16 v[118:133], v[170:173], v[50:53], v[118:133]
	v_exp_f32_e32 v147, v147
	v_add_f32_e32 v0, v0, v146
	v_add_f32_e32 v0, v0, v147
	v_mfma_f32_32x32x16_bf16 v[54:69], v[174:177], v[134:137], v[54:69]
	v_exp_f32_e32 v148, v148
	v_exp_f32_e32 v149, v149
	v_mfma_f32_32x32x16_bf16 v[70:85], v[178:181], v[134:137], v[70:85]
	v_add_f32_e32 v0, v0, v148
	v_add_f32_e32 v0, v0, v149
	v_mfma_f32_32x32x16_bf16 v[86:101], v[182:185], v[134:137], v[86:101]
	v_cvt_pk_bf16_f32 v142, v142, v143
	v_cvt_pk_bf16_f32 v143, v144, v145
	v_mfma_f32_32x32x16_bf16 v[102:117], v[188:191], v[134:137], v[102:117]
	v_cvt_pk_bf16_f32 v144, v146, v147
	v_cvt_pk_bf16_f32 v145, v148, v149
	s_nop 1
	v_mfma_f32_32x32x16_bf16 v[54:69], v[192:195], v[142:145], v[54:69]
	s_add_u32 s56, s56, 0x3000
	s_addc_u32 s57, s57, 0
	v_mfma_f32_32x32x16_bf16 v[70:85], v[196:199], v[142:145], v[70:85]
	s_add_u32 s98, s98, 0x3000
	s_addc_u32 s99, s99, 0
	v_mfma_f32_32x32x16_bf16 v[86:101], v[200:203], v[142:145], v[86:101]
	s_add_u32 s52, s52, 64
	s_addc_u32 s53, s53, 0
	v_mfma_f32_32x32x16_bf16 v[102:117], v[204:207], v[142:145], v[102:117]
	s_add_u32 s100, s100, 64
	s_addc_u32 s101, s101, 0
	s_waitcnt lgkmcnt(0)
	s_barrier
	ds_read_b128 v[150:153], v212 offset:0
	ds_read_b128 v[154:157], v212 offset:32
	ds_read_b128 v[158:161], v212 offset:64
	ds_read_b128 v[162:165], v212 offset:96
	ds_read_b128 v[166:169], v212 offset:128
	ds_read_b128 v[170:173], v212 offset:160
	s_waitcnt lgkmcnt(5)
	v_mfma_f32_32x32x16_bf16 v[134:149], v[150:153], v[6:9], 0
	ds_read_b128 v[150:153], v212 offset:192
	ds_read_b128 v[174:177], v213 offset:46080
	ds_read_b128 v[178:181], v213 offset:48640
	v_exp_f32_e32 v118, v118
	v_exp_f32_e32 v119, v119
	s_waitcnt lgkmcnt(7)
	v_mfma_f32_32x32x16_bf16 v[134:149], v[154:157], v[10:13], v[134:149]
	ds_read_b128 v[154:157], v212 offset:224
	ds_read_b128 v[182:185], v213 offset:51200
	ds_read_b128 v[188:191], v213 offset:53760
	v_add_f32_e32 v0, v0, v118
	v_add_f32_e32 v0, v0, v119
	s_waitcnt lgkmcnt(9)
	v_mfma_f32_32x32x16_bf16 v[134:149], v[158:161], v[14:17], v[134:149]
	ds_read_b128 v[158:161], v212 offset:256
	ds_read_b128 v[192:195], v213 offset:46112
	ds_read_b128 v[196:199], v213 offset:48672
	v_exp_f32_e32 v120, v120
	v_exp_f32_e32 v121, v121
	s_waitcnt lgkmcnt(11)
	v_mfma_f32_32x32x16_bf16 v[134:149], v[162:165], v[18:21], v[134:149]
	ds_read_b128 v[162:165], v212 offset:288
	ds_read_b128 v[200:203], v213 offset:51232
	ds_read_b128 v[204:207], v213 offset:53792
	v_add_f32_e32 v0, v0, v120
	v_add_f32_e32 v0, v0, v121
	s_waitcnt lgkmcnt(13)
	v_mfma_f32_32x32x16_bf16 v[134:149], v[166:169], v[22:25], v[134:149]
	ds_read_b128 v[166:169], v212 offset:320
	v_exp_f32_e32 v122, v122
	v_exp_f32_e32 v123, v123
	v_add_f32_e32 v0, v0, v122
	s_waitcnt lgkmcnt(13)
	v_mfma_f32_32x32x16_bf16 v[134:149], v[170:173], v[26:29], v[134:149]
	ds_read_b128 v[170:173], v212 offset:352
	v_add_f32_e32 v0, v0, v123
	v_exp_f32_e32 v124, v124
	v_exp_f32_e32 v125, v125
	s_waitcnt lgkmcnt(13)
	v_mfma_f32_32x32x16_bf16 v[134:149], v[150:153], v[30:33], v[134:149]
	s_waitcnt vmcnt(4)
	ds_write_b128 v244, v[208:211] offset:23040
	global_load_dwordx4 v[208:211], v248, s[56:57]
	v_add_f32_e32 v0, v0, v124
	v_add_f32_e32 v0, v0, v125
	v_cvt_pk_bf16_f32 v118, v118, v119
	s_waitcnt lgkmcnt(11)
	v_mfma_f32_32x32x16_bf16 v[134:149], v[154:157], v[34:37], v[134:149]
	s_waitcnt vmcnt(4)
	ds_write_b128 v245, v[216:219] offset:23040
	global_load_dwordx4 v[216:219], v248, s[98:99] offset:-4096
	v_cvt_pk_bf16_f32 v119, v120, v121
	v_cvt_pk_bf16_f32 v120, v122, v123
	v_cvt_pk_bf16_f32 v121, v124, v125
	s_waitcnt lgkmcnt(9)
	v_mfma_f32_32x32x16_bf16 v[134:149], v[158:161], v[38:41], v[134:149]
	s_waitcnt vmcnt(4)
	ds_write_b128 v246, v[220:223] offset:23040
	global_load_dwordx4 v[220:223], v248, s[98:99]
	v_exp_f32_e32 v126, v126
	v_exp_f32_e32 v127, v127
	v_add_f32_e32 v0, v0, v126
	s_waitcnt lgkmcnt(7)
	v_mfma_f32_32x32x16_bf16 v[134:149], v[162:165], v[42:45], v[134:149]
	s_waitcnt vmcnt(4)
	ds_write_b128 v247, v[236:239] offset:23040
	global_load_dwordx4 v[236:239], v235, s[52:53]
	v_add_f32_e32 v0, v0, v127
	v_exp_f32_e32 v128, v128
	v_exp_f32_e32 v129, v129
	s_waitcnt lgkmcnt(5)
	v_mfma_f32_32x32x16_bf16 v[134:149], v[166:169], v[46:49], v[134:149]
	s_waitcnt vmcnt(4)
	ds_write_b128 v247, v[240:243] offset:28160
	global_load_dwordx4 v[240:243], v235, s[100:101]
	v_add_f32_e32 v0, v0, v128
	v_add_f32_e32 v0, v0, v129
	v_exp_f32_e32 v130, v130
	s_waitcnt lgkmcnt(5)
	v_mfma_f32_32x32x16_bf16 v[134:149], v[170:173], v[50:53], v[134:149]
	v_exp_f32_e32 v131, v131
	v_add_f32_e32 v0, v0, v130
	v_add_f32_e32 v0, v0, v131
	v_mfma_f32_32x32x16_bf16 v[54:69], v[174:177], v[118:121], v[54:69]
	v_exp_f32_e32 v132, v132
	v_exp_f32_e32 v133, v133
	v_mfma_f32_32x32x16_bf16 v[70:85], v[178:181], v[118:121], v[70:85]
	v_add_f32_e32 v0, v0, v132
	v_add_f32_e32 v0, v0, v133
	v_mfma_f32_32x32x16_bf16 v[86:101], v[182:185], v[118:121], v[86:101]
	v_cvt_pk_bf16_f32 v126, v126, v127
	v_cvt_pk_bf16_f32 v127, v128, v129
	v_mfma_f32_32x32x16_bf16 v[102:117], v[188:191], v[118:121], v[102:117]
	v_cvt_pk_bf16_f32 v128, v130, v131
	v_cvt_pk_bf16_f32 v129, v132, v133
	s_nop 1
	v_mfma_f32_32x32x16_bf16 v[54:69], v[192:195], v[126:129], v[54:69]
	s_add_u32 s56, s56, 0x3000
	s_addc_u32 s57, s57, 0
	v_mfma_f32_32x32x16_bf16 v[70:85], v[196:199], v[126:129], v[70:85]
	s_add_u32 s98, s98, 0x3000
	s_addc_u32 s99, s99, 0
	v_mfma_f32_32x32x16_bf16 v[86:101], v[200:203], v[126:129], v[86:101]
	s_add_u32 s52, s52, 64
	s_addc_u32 s53, s53, 0
	v_mfma_f32_32x32x16_bf16 v[102:117], v[204:207], v[126:129], v[102:117]
	s_add_u32 s100, s100, 64
	s_addc_u32 s101, s101, 0
	s_waitcnt lgkmcnt(0)
	s_barrier
; __device__ __forceinline__ void attn_item(const Params& p, int b, int h, int qt, float shift, unsigned char* smem) {
;     ...
;   ATT_STEP(sB, sA, ntile - 1);
;   {
;     bf16x8 vfr[4];
;     ATT_VLOAD((ntile - 1) % 3, 0);
;     ATT_SHIFT(sB);
;     ATT_FINISH(sB, (ntile - 1) % 3);
	ds_read_b128 v[150:153], v212 offset:23040
	ds_read_b128 v[154:157], v212 offset:23072
	ds_read_b128 v[158:161], v212 offset:23104
	ds_read_b128 v[162:165], v212 offset:23136
	ds_read_b128 v[166:169], v212 offset:23168
	ds_read_b128 v[170:173], v212 offset:23200
	s_waitcnt lgkmcnt(5)
	v_mfma_f32_32x32x16_bf16 v[118:133], v[150:153], v[6:9], 0
	ds_read_b128 v[150:153], v212 offset:23232
	ds_read_b128 v[174:177], v213 offset:0
	ds_read_b128 v[178:181], v213 offset:2560
	v_exp_f32_e32 v134, v134
	v_exp_f32_e32 v135, v135
	s_waitcnt lgkmcnt(7)
	v_mfma_f32_32x32x16_bf16 v[118:133], v[154:157], v[10:13], v[118:133]
	ds_read_b128 v[154:157], v212 offset:23264
	ds_read_b128 v[182:185], v213 offset:5120
	ds_read_b128 v[188:191], v213 offset:7680
	v_add_f32_e32 v0, v0, v134
	v_add_f32_e32 v0, v0, v135
	s_waitcnt lgkmcnt(9)
	v_mfma_f32_32x32x16_bf16 v[118:133], v[158:161], v[14:17], v[118:133]
	ds_read_b128 v[158:161], v212 offset:23296
	ds_read_b128 v[192:195], v213 offset:32
	ds_read_b128 v[196:199], v213 offset:2592
	v_exp_f32_e32 v136, v136
	v_exp_f32_e32 v137, v137
	s_waitcnt lgkmcnt(11)
	v_mfma_f32_32x32x16_bf16 v[118:133], v[162:165], v[18:21], v[118:133]
	ds_read_b128 v[162:165], v212 offset:23328
	ds_read_b128 v[200:203], v213 offset:5152
	ds_read_b128 v[204:207], v213 offset:7712
	v_add_f32_e32 v0, v0, v136
	v_add_f32_e32 v0, v0, v137
	s_waitcnt lgkmcnt(13)
	v_mfma_f32_32x32x16_bf16 v[118:133], v[166:169], v[22:25], v[118:133]
	ds_read_b128 v[166:169], v212 offset:23360
	v_exp_f32_e32 v138, v138
	v_exp_f32_e32 v139, v139
	v_add_f32_e32 v0, v0, v138
	s_waitcnt lgkmcnt(13)
	v_mfma_f32_32x32x16_bf16 v[118:133], v[170:173], v[26:29], v[118:133]
	ds_read_b128 v[170:173], v212 offset:23392
	v_add_f32_e32 v0, v0, v139
	v_exp_f32_e32 v140, v140
	v_exp_f32_e32 v141, v141
	s_waitcnt lgkmcnt(13)
	v_mfma_f32_32x32x16_bf16 v[118:133], v[150:153], v[30:33], v[118:133]
	s_waitcnt vmcnt(4)
	ds_write_b128 v244, v[208:211] offset:46080
	v_add_f32_e32 v0, v0, v140
	v_add_f32_e32 v0, v0, v141
	v_cvt_pk_bf16_f32 v134, v134, v135
	s_waitcnt lgkmcnt(11)
	v_mfma_f32_32x32x16_bf16 v[118:133], v[154:157], v[34:37], v[118:133]
	s_waitcnt vmcnt(3)
	ds_write_b128 v245, v[216:219] offset:46080
	v_cvt_pk_bf16_f32 v135, v136, v137
	v_cvt_pk_bf16_f32 v136, v138, v139
	v_cvt_pk_bf16_f32 v137, v140, v141
	s_waitcnt lgkmcnt(9)
	v_mfma_f32_32x32x16_bf16 v[118:133], v[158:161], v[38:41], v[118:133]
	s_waitcnt vmcnt(2)
	ds_write_b128 v246, v[220:223] offset:46080
	v_exp_f32_e32 v142, v142
	v_exp_f32_e32 v143, v143
	v_add_f32_e32 v0, v0, v142
	s_waitcnt lgkmcnt(7)
	v_mfma_f32_32x32x16_bf16 v[118:133], v[162:165], v[42:45], v[118:133]
	s_waitcnt vmcnt(1)
	ds_write_b128 v247, v[236:239] offset:46080
	v_add_f32_e32 v0, v0, v143
	v_exp_f32_e32 v144, v144
	v_exp_f32_e32 v145, v145
	s_waitcnt lgkmcnt(5)
	v_mfma_f32_32x32x16_bf16 v[118:133], v[166:169], v[46:49], v[118:133]
	s_waitcnt vmcnt(0)
	ds_write_b128 v247, v[240:243] offset:51200
	v_add_f32_e32 v0, v0, v144
	v_add_f32_e32 v0, v0, v145
	v_exp_f32_e32 v146, v146
	s_waitcnt lgkmcnt(5)
	v_mfma_f32_32x32x16_bf16 v[118:133], v[170:173], v[50:53], v[118:133]
	v_exp_f32_e32 v147, v147
	v_add_f32_e32 v0, v0, v146
	v_add_f32_e32 v0, v0, v147
	v_mfma_f32_32x32x16_bf16 v[54:69], v[174:177], v[134:137], v[54:69]
	v_exp_f32_e32 v148, v148
	v_exp_f32_e32 v149, v149
	v_mfma_f32_32x32x16_bf16 v[70:85], v[178:181], v[134:137], v[70:85]
	v_add_f32_e32 v0, v0, v148
	v_add_f32_e32 v0, v0, v149
	v_mfma_f32_32x32x16_bf16 v[86:101], v[182:185], v[134:137], v[86:101]
	v_cvt_pk_bf16_f32 v142, v142, v143
	v_cvt_pk_bf16_f32 v143, v144, v145
	v_mfma_f32_32x32x16_bf16 v[102:117], v[188:191], v[134:137], v[102:117]
	v_cvt_pk_bf16_f32 v144, v146, v147
	v_cvt_pk_bf16_f32 v145, v148, v149
	s_nop 1
	v_mfma_f32_32x32x16_bf16 v[54:69], v[192:195], v[142:145], v[54:69]
	v_mfma_f32_32x32x16_bf16 v[70:85], v[196:199], v[142:145], v[70:85]
	v_mfma_f32_32x32x16_bf16 v[86:101], v[200:203], v[142:145], v[86:101]
	v_mfma_f32_32x32x16_bf16 v[102:117], v[204:207], v[142:145], v[102:117]
	s_waitcnt lgkmcnt(0)
	s_barrier
	ds_read_b128 v[150:153], v212 offset:46080
	ds_read_b128 v[154:157], v212 offset:46112
	ds_read_b128 v[158:161], v212 offset:46144
	ds_read_b128 v[162:165], v212 offset:46176
	ds_read_b128 v[166:169], v212 offset:46208
	ds_read_b128 v[170:173], v212 offset:46240
	s_waitcnt lgkmcnt(5)
	v_mfma_f32_32x32x16_bf16 v[134:149], v[150:153], v[6:9], 0
	ds_read_b128 v[150:153], v212 offset:46272
	ds_read_b128 v[174:177], v213 offset:23040
	ds_read_b128 v[178:181], v213 offset:25600
	v_exp_f32_e32 v118, v118
	v_exp_f32_e32 v119, v119
	s_waitcnt lgkmcnt(7)
	v_mfma_f32_32x32x16_bf16 v[134:149], v[154:157], v[10:13], v[134:149]
	ds_read_b128 v[154:157], v212 offset:46304
	ds_read_b128 v[182:185], v213 offset:28160
	ds_read_b128 v[188:191], v213 offset:30720
	v_add_f32_e32 v0, v0, v118
	v_add_f32_e32 v0, v0, v119
	s_waitcnt lgkmcnt(9)
	v_mfma_f32_32x32x16_bf16 v[134:149], v[158:161], v[14:17], v[134:149]
	ds_read_b128 v[158:161], v212 offset:46336
	ds_read_b128 v[192:195], v213 offset:23072
	ds_read_b128 v[196:199], v213 offset:25632
	v_exp_f32_e32 v120, v120
	v_exp_f32_e32 v121, v121
	s_waitcnt lgkmcnt(11)
	v_mfma_f32_32x32x16_bf16 v[134:149], v[162:165], v[18:21], v[134:149]
	ds_read_b128 v[162:165], v212 offset:46368
	ds_read_b128 v[200:203], v213 offset:28192
	ds_read_b128 v[204:207], v213 offset:30752
	v_add_f32_e32 v0, v0, v120
	v_add_f32_e32 v0, v0, v121
	s_waitcnt lgkmcnt(13)
	v_mfma_f32_32x32x16_bf16 v[134:149], v[166:169], v[22:25], v[134:149]
	ds_read_b128 v[166:169], v212 offset:46400
	v_exp_f32_e32 v122, v122
	v_exp_f32_e32 v123, v123
	v_add_f32_e32 v0, v0, v122
	s_waitcnt lgkmcnt(13)
; __device__ __forceinline__ void attn_item(const Params& p, int b, int h, int qt, float shift, unsigned char* smem) {
;     ...
;   ATT_STEP(sB, sA, ntile - 1);
;   {
;     bf16x8 vfr[4];
;     ATT_VLOAD((ntile - 1) % 3, 0);
;     ATT_SHIFT(sB);
;     ATT_FINISH(sB, (ntile - 1) % 3);
	v_mfma_f32_32x32x16_bf16 v[134:149], v[170:173], v[26:29], v[134:149]
	ds_read_b128 v[170:173], v212 offset:46432
	v_add_f32_e32 v0, v0, v123
	v_exp_f32_e32 v124, v124
	v_exp_f32_e32 v125, v125
	s_waitcnt lgkmcnt(13)
	v_mfma_f32_32x32x16_bf16 v[134:149], v[150:153], v[30:33], v[134:149]
	v_add_f32_e32 v0, v0, v124
	v_add_f32_e32 v0, v0, v125
	v_cvt_pk_bf16_f32 v118, v118, v119
	s_waitcnt lgkmcnt(10)
	v_mfma_f32_32x32x16_bf16 v[134:149], v[154:157], v[34:37], v[134:149]
	v_cvt_pk_bf16_f32 v119, v120, v121
	v_cvt_pk_bf16_f32 v120, v122, v123
	v_cvt_pk_bf16_f32 v121, v124, v125
	s_waitcnt lgkmcnt(7)
	v_mfma_f32_32x32x16_bf16 v[134:149], v[158:161], v[38:41], v[134:149]
	v_exp_f32_e32 v126, v126
	v_exp_f32_e32 v127, v127
	v_add_f32_e32 v0, v0, v126
	s_waitcnt lgkmcnt(4)
	v_mfma_f32_32x32x16_bf16 v[134:149], v[162:165], v[42:45], v[134:149]
	v_add_f32_e32 v0, v0, v127
	v_exp_f32_e32 v128, v128
	v_exp_f32_e32 v129, v129
	s_waitcnt lgkmcnt(1)
	v_mfma_f32_32x32x16_bf16 v[134:149], v[166:169], v[46:49], v[134:149]
	v_add_f32_e32 v0, v0, v128
	v_add_f32_e32 v0, v0, v129
	v_exp_f32_e32 v130, v130
	s_waitcnt lgkmcnt(0)
	v_mfma_f32_32x32x16_bf16 v[134:149], v[170:173], v[50:53], v[134:149]
	v_exp_f32_e32 v131, v131
	v_add_f32_e32 v0, v0, v130
	v_add_f32_e32 v0, v0, v131
	v_mfma_f32_32x32x16_bf16 v[54:69], v[174:177], v[118:121], v[54:69]
	v_exp_f32_e32 v132, v132
	v_exp_f32_e32 v133, v133
	v_mfma_f32_32x32x16_bf16 v[70:85], v[178:181], v[118:121], v[70:85]
	v_add_f32_e32 v0, v0, v132
	v_add_f32_e32 v0, v0, v133
	v_mfma_f32_32x32x16_bf16 v[86:101], v[182:185], v[118:121], v[86:101]
	v_cvt_pk_bf16_f32 v126, v126, v127
	v_cvt_pk_bf16_f32 v127, v128, v129
	v_mfma_f32_32x32x16_bf16 v[102:117], v[188:191], v[118:121], v[102:117]
	v_cvt_pk_bf16_f32 v128, v130, v131
	v_cvt_pk_bf16_f32 v129, v132, v133
	s_nop 1
	v_mfma_f32_32x32x16_bf16 v[54:69], v[192:195], v[126:129], v[54:69]
	v_mfma_f32_32x32x16_bf16 v[70:85], v[196:199], v[126:129], v[70:85]
	v_mfma_f32_32x32x16_bf16 v[86:101], v[200:203], v[126:129], v[86:101]
	v_mfma_f32_32x32x16_bf16 v[102:117], v[204:207], v[126:129], v[102:117]
	s_waitcnt lgkmcnt(0)
	s_barrier
; __device__ __forceinline__ void attn_item(const Params& p, int b, int h, int qt, float shift, unsigned char* smem) {
;     ...
;   {
;     bf16x8 vfr[4];
;     ATT_VLOAD((ntile - 1) % 3, 0);
;     ATT_SHIFT(sB);
;     ATT_FINISH(sB, (ntile - 1) % 3);
;   }
;   __syncthreads();
;     ...
; #pragma unroll
;   for (int qi = 0; qi < 2; ++qi) {
;     float ls = qi ? lrun1 : lrun0;
;     ls += __shfl_xor(ls, 16);
;     ls += __shfl_xor(ls, 32);
;     const float inv = 1.f / ls;
;     const int pos = qt * 128 + wid * 32 + qi * 16 + l16;
;     const int row = (pos < CTX) ? (T_LAT + b * CTX + pos) : (b * SEQ + pos - CTX);
;     u16* orow = p.YM + (size_t)row * 1024 + 512 + h * 128 + quad * 4;
; #pragma unroll
;     for (int vt = 0; vt < 8; ++vt) {
;       u32x2 pk;
;       pk.x = pack2(o[vt][qi][0] * inv, o[vt][qi][1] * inv);
;       pk.y = pack2(o[vt][qi][2] * inv, o[vt][qi][3] * inv);
;       *(u32x2*)(orow + vt * 16) = pk;
;     }
;   }
	ds_read_b128 v[174:177], v213 offset:46080
	ds_read_b128 v[178:181], v213 offset:48640
	ds_read_b128 v[182:185], v213 offset:51200
	ds_read_b128 v[188:191], v213 offset:53760
	ds_read_b128 v[192:195], v213 offset:46112
	ds_read_b128 v[196:199], v213 offset:48672
	ds_read_b128 v[200:203], v213 offset:51232
	ds_read_b128 v[204:207], v213 offset:53792
	v_exp_f32_e32 v134, v134
	v_exp_f32_e32 v135, v135
	v_add_f32_e32 v0, v0, v134
	v_add_f32_e32 v0, v0, v135
	v_exp_f32_e32 v136, v136
	v_exp_f32_e32 v137, v137
	v_add_f32_e32 v0, v0, v136
	v_add_f32_e32 v0, v0, v137
	v_exp_f32_e32 v138, v138
	v_exp_f32_e32 v139, v139
	v_add_f32_e32 v0, v0, v138
	v_add_f32_e32 v0, v0, v139
	v_exp_f32_e32 v140, v140
	v_exp_f32_e32 v141, v141
	v_add_f32_e32 v0, v0, v140
	v_add_f32_e32 v0, v0, v141
	v_cvt_pk_bf16_f32 v134, v134, v135
	v_cvt_pk_bf16_f32 v135, v136, v137
	v_cvt_pk_bf16_f32 v136, v138, v139
	v_cvt_pk_bf16_f32 v137, v140, v141
	v_exp_f32_e32 v142, v142
	v_exp_f32_e32 v143, v143
	v_add_f32_e32 v0, v0, v142
	v_add_f32_e32 v0, v0, v143
	v_exp_f32_e32 v144, v144
	v_exp_f32_e32 v145, v145
	v_add_f32_e32 v0, v0, v144
	v_add_f32_e32 v0, v0, v145
	v_exp_f32_e32 v146, v146
	v_exp_f32_e32 v147, v147
	v_add_f32_e32 v0, v0, v146
	v_add_f32_e32 v0, v0, v147
	v_exp_f32_e32 v148, v148
	v_exp_f32_e32 v149, v149
	v_add_f32_e32 v0, v0, v148
	v_add_f32_e32 v0, v0, v149
	v_cvt_pk_bf16_f32 v142, v142, v143
	v_cvt_pk_bf16_f32 v143, v144, v145
	v_cvt_pk_bf16_f32 v144, v146, v147
	v_cvt_pk_bf16_f32 v145, v148, v149
	s_nop 1
	s_waitcnt lgkmcnt(7)
	v_mfma_f32_32x32x16_bf16 v[54:69], v[174:177], v[134:137], v[54:69]
	s_waitcnt lgkmcnt(6)
	v_mfma_f32_32x32x16_bf16 v[70:85], v[178:181], v[134:137], v[70:85]
	s_waitcnt lgkmcnt(5)
	v_mfma_f32_32x32x16_bf16 v[86:101], v[182:185], v[134:137], v[86:101]
	s_waitcnt lgkmcnt(4)
	v_mfma_f32_32x32x16_bf16 v[102:117], v[188:191], v[134:137], v[102:117]
	s_waitcnt lgkmcnt(3)
	v_mfma_f32_32x32x16_bf16 v[54:69], v[192:195], v[142:145], v[54:69]
	s_waitcnt lgkmcnt(2)
	v_mfma_f32_32x32x16_bf16 v[70:85], v[196:199], v[142:145], v[70:85]
	s_waitcnt lgkmcnt(1)
	v_mfma_f32_32x32x16_bf16 v[86:101], v[200:203], v[142:145], v[86:101]
	s_waitcnt lgkmcnt(0)
	v_mfma_f32_32x32x16_bf16 v[102:117], v[204:207], v[142:145], v[102:117]
	ds_bpermute_b32 v118, v229, v0
	v_and_b32_e32 v119, 31, v187
	v_bfe_u32 v120, v187, 5, 1
	v_lshlrev_b32_e32 v119, 11, v119
	v_lshl_add_u32 v123, v120, 3, v119
	s_waitcnt lgkmcnt(0)
	v_add_f32_e32 v0, v0, v118
	v_div_scale_f32 v118, s[0:1], v0, v0, 1.0
	v_rcp_f32_e32 v119, v118
	s_nop 0
	v_fma_f32 v120, -v118, v119, 1.0
	v_fmac_f32_e32 v119, v120, v119
	v_div_scale_f32 v120, vcc, 1.0, v0, 1.0
	v_mul_f32_e32 v121, v120, v119
	v_fma_f32 v122, -v118, v121, v120
	v_fmac_f32_e32 v121, v122, v119
	v_fma_f32 v118, -v118, v121, v120
	v_div_fmas_f32 v118, v118, v119, v121
	v_div_fixup_f32 v0, v118, v0, 1.0
	s_nop 4
	v_mul_f32_e32 v54, v54, v0
	v_mul_f32_e32 v55, v55, v0
	v_mul_f32_e32 v56, v56, v0
	v_mul_f32_e32 v57, v57, v0
	v_cvt_pk_bf16_f32 v54, v54, v55
	v_cvt_pk_bf16_f32 v55, v56, v57
	global_store_dwordx2 v123, v[54:55], s[88:89] offset:0
	v_mul_f32_e32 v58, v58, v0
	v_mul_f32_e32 v59, v59, v0
	v_mul_f32_e32 v60, v60, v0
	v_mul_f32_e32 v61, v61, v0
	v_cvt_pk_bf16_f32 v58, v58, v59
	v_cvt_pk_bf16_f32 v59, v60, v61
	global_store_dwordx2 v123, v[58:59], s[88:89] offset:16
	v_mul_f32_e32 v62, v62, v0
	v_mul_f32_e32 v63, v63, v0
	v_mul_f32_e32 v64, v64, v0
	v_mul_f32_e32 v65, v65, v0
	v_cvt_pk_bf16_f32 v62, v62, v63
	v_cvt_pk_bf16_f32 v63, v64, v65
	global_store_dwordx2 v123, v[62:63], s[88:89] offset:32
	v_mul_f32_e32 v66, v66, v0
	v_mul_f32_e32 v67, v67, v0
	v_mul_f32_e32 v68, v68, v0
	v_mul_f32_e32 v69, v69, v0
	v_cvt_pk_bf16_f32 v66, v66, v67
	v_cvt_pk_bf16_f32 v67, v68, v69
	global_store_dwordx2 v123, v[66:67], s[88:89] offset:48
	v_mul_f32_e32 v70, v70, v0
	v_mul_f32_e32 v71, v71, v0
	v_mul_f32_e32 v72, v72, v0
	v_mul_f32_e32 v73, v73, v0
	v_cvt_pk_bf16_f32 v70, v70, v71
	v_cvt_pk_bf16_f32 v71, v72, v73
	global_store_dwordx2 v123, v[70:71], s[88:89] offset:64
	v_mul_f32_e32 v74, v74, v0
	v_mul_f32_e32 v75, v75, v0
	v_mul_f32_e32 v76, v76, v0
	v_mul_f32_e32 v77, v77, v0
	v_cvt_pk_bf16_f32 v74, v74, v75
	v_cvt_pk_bf16_f32 v75, v76, v77
	global_store_dwordx2 v123, v[74:75], s[88:89] offset:80
	v_mul_f32_e32 v78, v78, v0
	v_mul_f32_e32 v79, v79, v0
	v_mul_f32_e32 v80, v80, v0
	v_mul_f32_e32 v81, v81, v0
	v_cvt_pk_bf16_f32 v78, v78, v79
	v_cvt_pk_bf16_f32 v79, v80, v81
	global_store_dwordx2 v123, v[78:79], s[88:89] offset:96
	v_mul_f32_e32 v82, v82, v0
	v_mul_f32_e32 v83, v83, v0
	v_mul_f32_e32 v84, v84, v0
	v_mul_f32_e32 v85, v85, v0
	v_cvt_pk_bf16_f32 v82, v82, v83
	v_cvt_pk_bf16_f32 v83, v84, v85
	global_store_dwordx2 v123, v[82:83], s[88:89] offset:112
	v_mul_f32_e32 v86, v86, v0
	v_mul_f32_e32 v87, v87, v0
	v_mul_f32_e32 v88, v88, v0
	v_mul_f32_e32 v89, v89, v0
	v_cvt_pk_bf16_f32 v86, v86, v87
	v_cvt_pk_bf16_f32 v87, v88, v89
	global_store_dwordx2 v123, v[86:87], s[88:89] offset:128
	v_mul_f32_e32 v90, v90, v0
	v_mul_f32_e32 v91, v91, v0
	v_mul_f32_e32 v92, v92, v0
	v_mul_f32_e32 v93, v93, v0
	v_cvt_pk_bf16_f32 v90, v90, v91
	v_cvt_pk_bf16_f32 v91, v92, v93
	global_store_dwordx2 v123, v[90:91], s[88:89] offset:144
	v_mul_f32_e32 v94, v94, v0
	v_mul_f32_e32 v95, v95, v0
	v_mul_f32_e32 v96, v96, v0
	v_mul_f32_e32 v97, v97, v0
	v_cvt_pk_bf16_f32 v94, v94, v95
	v_cvt_pk_bf16_f32 v95, v96, v97
	global_store_dwordx2 v123, v[94:95], s[88:89] offset:160
	v_mul_f32_e32 v98, v98, v0
	v_mul_f32_e32 v99, v99, v0
	v_mul_f32_e32 v100, v100, v0
	v_mul_f32_e32 v101, v101, v0
	v_cvt_pk_bf16_f32 v98, v98, v99
	v_cvt_pk_bf16_f32 v99, v100, v101
	global_store_dwordx2 v123, v[98:99], s[88:89] offset:176
	v_mul_f32_e32 v102, v102, v0
	v_mul_f32_e32 v103, v103, v0
	v_mul_f32_e32 v104, v104, v0
	v_mul_f32_e32 v105, v105, v0
	v_cvt_pk_bf16_f32 v102, v102, v103
	v_cvt_pk_bf16_f32 v103, v104, v105
	global_store_dwordx2 v123, v[102:103], s[88:89] offset:192
	v_mul_f32_e32 v106, v106, v0
	v_mul_f32_e32 v107, v107, v0
	v_mul_f32_e32 v108, v108, v0
	v_mul_f32_e32 v109, v109, v0
	v_cvt_pk_bf16_f32 v106, v106, v107
	v_cvt_pk_bf16_f32 v107, v108, v109
	global_store_dwordx2 v123, v[106:107], s[88:89] offset:208
	v_mul_f32_e32 v110, v110, v0
	v_mul_f32_e32 v111, v111, v0
	v_mul_f32_e32 v112, v112, v0
	v_mul_f32_e32 v113, v113, v0
	v_cvt_pk_bf16_f32 v110, v110, v111
	v_cvt_pk_bf16_f32 v111, v112, v113
	global_store_dwordx2 v123, v[110:111], s[88:89] offset:224
	v_mul_f32_e32 v114, v114, v0
	v_mul_f32_e32 v115, v115, v0
	v_mul_f32_e32 v116, v116, v0
	v_mul_f32_e32 v117, v117, v0
	v_cvt_pk_bf16_f32 v114, v114, v115
	v_cvt_pk_bf16_f32 v115, v116, v117
	global_store_dwordx2 v123, v[114:115], s[88:89] offset:240
	s_waitcnt lgkmcnt(0)
	s_barrier
	s_mov_b32 s47, s95
	s_add_i32 s50, s50, s3
	s_cmp_gt_i32 s50, 63
	s_cbranch_scc0 .LBB0_766
	s_branch .LBB0_776


; __global__ void __launch_bounds__(256, 2) fwd_megakernel(Params p_unused) {
;   const Params& p = *(const Params*)__builtin_amdgcn_kernarg_segment_ptr();
;   __shared__ __attribute__((aligned(16))) unsigned char smem[SMEM_BYTES];
	.amdhsa_kernel _Z14fwd_megakernel6Params
		.amdhsa_group_segment_fixed_size 71696
		.amdhsa_private_segment_fixed_size 0
		.amdhsa_kernarg_size 688
		.amdhsa_user_sgpr_count 2
		.amdhsa_user_sgpr_dispatch_ptr 0
		.amdhsa_user_sgpr_queue_ptr 0
		.amdhsa_user_sgpr_kernarg_segment_ptr 1
		.amdhsa_user_sgpr_dispatch_id 0
		.amdhsa_user_sgpr_kernarg_preload_length 0
		.amdhsa_user_sgpr_kernarg_preload_offset 0
		.amdhsa_user_sgpr_private_segment_size 0
		.amdhsa_uses_dynamic_stack 0
		.amdhsa_enable_private_segment 0
		.amdhsa_system_sgpr_workgroup_id_x 1
		.amdhsa_system_sgpr_workgroup_id_y 0
		.amdhsa_system_sgpr_workgroup_id_z 0
		.amdhsa_system_sgpr_workgroup_info 0
		.amdhsa_system_vgpr_workitem_id 2
		.amdhsa_next_free_vgpr 256
		.amdhsa_next_free_sgpr 102
		.amdhsa_accum_offset 256
		.amdhsa_reserve_vcc 1
		.amdhsa_float_round_mode_32 0
		.amdhsa_float_round_mode_16_64 0
		.amdhsa_float_denorm_mode_32 3
		.amdhsa_float_denorm_mode_16_64 3
		.amdhsa_dx10_clamp 1
		.amdhsa_ieee_mode 1
		.amdhsa_fp16_overflow 0
		.amdhsa_tg_split 0
		.amdhsa_exception_fp_ieee_invalid_op 0
		.amdhsa_exception_fp_denorm_src 0
		.amdhsa_exception_fp_ieee_div_zero 0
		.amdhsa_exception_fp_ieee_overflow 0
		.amdhsa_exception_fp_ieee_underflow 0
		.amdhsa_exception_fp_ieee_inexact 0
		.amdhsa_exception_int_div_zero 0
	.end_amdhsa_kernel

; __global__ void __launch_bounds__(256, 2) fwd_megakernel(Params p_unused) {
;   const Params& p = *(const Params*)__builtin_amdgcn_kernarg_segment_ptr();
;   __shared__ __attribute__((aligned(16))) unsigned char smem[SMEM_BYTES];
amdhsa.kernels:
  - .agpr_count:     0
    .args:
      - .offset:         0
        .size:           432
        .value_kind:     by_value
      - .offset:         432
        .size:           4
        .value_kind:     hidden_block_count_x
      - .offset:         436
        .size:           4
        .value_kind:     hidden_block_count_y
      - .offset:         440
        .size:           4
        .value_kind:     hidden_block_count_z
      - .offset:         444
        .size:           2
        .value_kind:     hidden_group_size_x
      - .offset:         446
        .size:           2
        .value_kind:     hidden_group_size_y
      - .offset:         448
        .size:           2
        .value_kind:     hidden_group_size_z
      - .offset:         450
        .size:           2
        .value_kind:     hidden_remainder_x
      - .offset:         452
        .size:           2
        .value_kind:     hidden_remainder_y
      - .offset:         454
        .size:           2
        .value_kind:     hidden_remainder_z
      - .offset:         472
        .size:           8
        .value_kind:     hidden_global_offset_x
      - .offset:         480
        .size:           8
        .value_kind:     hidden_global_offset_y
      - .offset:         488
        .size:           8
        .value_kind:     hidden_global_offset_z
      - .offset:         496
        .size:           2
        .value_kind:     hidden_grid_dims
      - .offset:         520
        .size:           8
        .value_kind:     hidden_multigrid_sync_arg
    .group_segment_fixed_size: 71696
    .kernarg_segment_align: 8
    .kernarg_segment_size: 688
    .language:       OpenCL C
    .language_version:
      - 2
      - 0
    .max_flat_workgroup_size: 256
    .name:           _Z14fwd_megakernel6Params
    .private_segment_fixed_size: 0
    .sgpr_count:     108
    .sgpr_spill_count: 65
    .symbol:         _Z14fwd_megakernel6Params.kd
    .uniform_work_group_size: 1
    .uses_dynamic_stack: false
    .vgpr_count:     256
    .vgpr_spill_count: 0
    .wavefront_size: 64
